# up GEMM: half of each tile's H stores (the ai=1 rows) are held in registers and issued one per K-iteration in iterations 1-4 of the next tile (separate loop bodies with vmcnt 8/9/9/9), flushed after t
# baseline (speedup 1.0000x reference)
; #define PG8_STAGE(bufoff, gbase, voff) do { _Pragma("unroll") for (int _i = 0; _i < 2; ++_i) \
;         __builtin_amdgcn_global_load_lds((const unsigned*)((const char*)(gbase) + (voff)[_i]), (PG8_LAS unsigned*)(lds + (bufoff) + ldsw + _i * 8192), 16, 0, 0); } while (0)
; #define PG8_LDA(dst, b, h) do { _Pragma("unroll") for (int m = 0; m < 4; ++m) _Pragma("unroll") for (int k = 0; k < 2; ++k) dst[m][k] = *(const PG8_LAS bf16x8*)(lds + PG8_SA(b, h) + aoff + m * 2048 + k * 1024); } while (0)
; #define PG8_LDB(dst, b, h) do { _Pragma("unroll") for (int n = 0; n < 2; ++n) _Pragma("unroll") for (int k = 0; k < 2; ++k) dst[n][k] = *(const PG8_LAS bf16x8*)(lds + PG8_SB(b, h) + boff + n * 2048 + k * 1024); } while (0)
; #define PG8_MMA(ai, bj, At, Bt) do { __builtin_amdgcn_s_setprio(1); _Pragma("unroll") for (int m = 0; m < 4; ++m) _Pragma("unroll") for (int n = 0; n < 2; ++n) _Pragma("unroll") for (int k = 0; k < 2; ++k) \
;         acc[ai][bj][m][n] = __builtin_amdgcn_mfma_f32_16x16x32_bf16(Bt[n][k], At[m][k], acc[ai][bj][m][n], 0, 0, 0); __builtin_amdgcn_s_setprio(0); } while (0)
; #define PG8_WAIT_V(n) asm volatile("s_waitcnt vmcnt(" #n ")" ::: "memory")
; #define PG8_WAIT_L(n) asm volatile("s_waitcnt lgkmcnt(" #n ")" ::: "memory")
; #define PG8_BAR __builtin_amdgcn_s_barrier()
; template <class Epi, class Sched, bool ALIGN_EPI = false, bool SP2 = false>
; __device__ __forceinline__ void gemm_phase(PG8_LAS unsigned char* lds, const Gemm g, const Sched& S, const Epi& E) {
;     ...
;             const char* a1 = cA + (size_t)(t + 1) * kstep;
;             const char* a2 = last ? nA : cA + (size_t)(t + 2) * kstep; const char* b2 = last ? nB : cB + (size_t)(t + 2) * kstep;
;             const char* a3 = a2 + kstep; const char* b3 = b2 + kstep;
;             if (last && has_next) S.a_ready(nxt);
;             if constexpr (SP2) {
;             PG8_LDB(B0, 0, 0); PG8_LDB(B1, 0, 1); PG8_SCHED; PG8_LDA(At, 0, 0); PG8_STAGE(PG8_SA(1, 1), a1 + hstep, voffA);
;             PG8_WAIT_V(8); PG8_WAIT_L(0); PG8_BAR; PG8_MMA(0, 0, At, B0); PG8_MMA(0, 1, At, B1); PG8_BAR; PG8_SCHED;
;             PG8_LDA(At, 0, 1); PG8_STAGE(PG8_SB(0, 0), b2, voffB); PG8_STAGE(PG8_SB(0, 1), b2 + hstep, voffB); PG8_STAGE(PG8_SA(0, 0), a2, voffA);
;             PG8_WAIT_V(8); PG8_WAIT_L(0); PG8_BAR; PG8_MMA(1, 0, At, B0); PG8_MMA(1, 1, At, B1); PG8_BAR; PG8_SCHED;
.Lup_peel:
	ds_read_b128 v[140:143], v254
	ds_read_b128 v[168:171], v254 offset:1024
	ds_read_b128 v[172:175], v254 offset:2048
	ds_read_b128 v[176:179], v254 offset:3072
	ds_read_b128 v[180:183], v254 offset:16384
	ds_read_b128 v[184:187], v254 offset:17408
	ds_read_b128 v[188:191], v254 offset:18432
	ds_read_b128 v[210:213], v254 offset:19456
	s_add_u32 s16, s14, 0xfffc0080
	s_addc_u32 s17, s15, -1
	s_cmp_eq_u32 s53, 12
	s_cselect_b32 s19, s7, s17
	s_cselect_b32 s18, s49, s16
	s_cselect_b32 s17, s5, s52
	s_cselect_b32 s16, s50, s51
	s_mov_b32 m0, s43
	ds_read_b128 v[214:217], v165
	ds_read_b128 v[218:221], v165 offset:1024
	ds_read_b128 v[222:225], v165 offset:2048
	ds_read_b128 v[226:229], v165 offset:3072
	ds_read_b128 v[230:233], v165 offset:4096
	ds_read_b128 v[234:237], v165 offset:5120
	ds_read_b128 v[238:241], v165 offset:6144
	ds_read_b128 v[242:245], v165 offset:7168
	global_load_lds_dwordx4 v136, s[14:15]
	s_mov_b32 m0, s44
	s_nop 0
	global_load_lds_dwordx4 v138, s[14:15]
	s_waitcnt vmcnt(8)
	s_waitcnt lgkmcnt(0)
	s_barrier
	s_setprio 1
	v_mfma_f32_16x16x32_bf16 v[124:127], v[140:143], v[214:217], 0
	v_mfma_f32_16x16x32_bf16 v[116:119], v[172:175], v[214:217], 0
	v_mfma_f32_16x16x32_bf16 v[108:111], v[140:143], v[222:225], 0
	v_mfma_f32_16x16x32_bf16 v[100:103], v[172:175], v[222:225], 0
	v_mfma_f32_16x16x32_bf16 v[92:95], v[140:143], v[230:233], 0
	v_mfma_f32_16x16x32_bf16 v[84:87], v[172:175], v[230:233], 0
	v_mfma_f32_16x16x32_bf16 v[76:79], v[140:143], v[238:241], 0
	v_mfma_f32_16x16x32_bf16 v[68:71], v[172:175], v[238:241], 0
	v_mfma_f32_16x16x32_bf16 v[124:127], v[168:171], v[218:221], v[124:127]
	v_mfma_f32_16x16x32_bf16 v[116:119], v[176:179], v[218:221], v[116:119]
	v_mfma_f32_16x16x32_bf16 v[108:111], v[168:171], v[226:229], v[108:111]
	v_mfma_f32_16x16x32_bf16 v[100:103], v[176:179], v[226:229], v[100:103]
	v_mfma_f32_16x16x32_bf16 v[92:95], v[168:171], v[234:237], v[92:95]
	v_mfma_f32_16x16x32_bf16 v[84:87], v[176:179], v[234:237], v[84:87]
	v_mfma_f32_16x16x32_bf16 v[76:79], v[168:171], v[242:245], v[76:79]
	v_mfma_f32_16x16x32_bf16 v[68:71], v[176:179], v[242:245], v[68:71]
	v_mfma_f32_16x16x32_bf16 v[120:123], v[180:183], v[214:217], 0
	v_mfma_f32_16x16x32_bf16 v[112:115], v[188:191], v[214:217], 0
	v_mfma_f32_16x16x32_bf16 v[104:107], v[180:183], v[222:225], 0
	v_mfma_f32_16x16x32_bf16 v[96:99], v[188:191], v[222:225], 0
	v_mfma_f32_16x16x32_bf16 v[88:91], v[180:183], v[230:233], 0
	v_mfma_f32_16x16x32_bf16 v[80:83], v[188:191], v[230:233], 0
	v_mfma_f32_16x16x32_bf16 v[72:75], v[180:183], v[238:241], 0
	v_mfma_f32_16x16x32_bf16 v[64:67], v[188:191], v[238:241], 0
	v_mfma_f32_16x16x32_bf16 v[120:123], v[184:187], v[218:221], v[120:123]
	v_mfma_f32_16x16x32_bf16 v[112:115], v[210:213], v[218:221], v[112:115]
	v_mfma_f32_16x16x32_bf16 v[104:107], v[184:187], v[226:229], v[104:107]
	v_mfma_f32_16x16x32_bf16 v[96:99], v[210:213], v[226:229], v[96:99]
	v_mfma_f32_16x16x32_bf16 v[88:91], v[184:187], v[234:237], v[88:91]
	v_mfma_f32_16x16x32_bf16 v[80:83], v[210:213], v[234:237], v[80:83]
	v_mfma_f32_16x16x32_bf16 v[72:75], v[184:187], v[242:245], v[72:75]
	v_mfma_f32_16x16x32_bf16 v[64:67], v[210:213], v[242:245], v[64:67]
	s_setprio 0
	s_barrier
	s_mov_b32 m0, s27
	s_add_u32 s54, s16, 0x40000
	s_addc_u32 s55, s17, 0
	ds_read_b128 v[214:217], v165 offset:16384
	ds_read_b128 v[218:221], v165 offset:17408
	ds_read_b128 v[222:225], v165 offset:18432
	ds_read_b128 v[226:229], v165 offset:19456
	ds_read_b128 v[230:233], v165 offset:20480
	ds_read_b128 v[234:237], v165 offset:21504
	ds_read_b128 v[238:241], v165 offset:22528
	ds_read_b128 v[242:245], v165 offset:23552
	global_load_lds_dwordx4 v132, s[16:17]
	s_mov_b32 m0, s28
	s_nop 0
	global_load_lds_dwordx4 v128, s[16:17]
	s_mov_b32 m0, s29
	s_nop 0
	global_load_lds_dwordx4 v132, s[54:55]
	s_mov_b32 m0, s30
	s_nop 0
	global_load_lds_dwordx4 v128, s[54:55]
	s_mov_b32 m0, s22
	s_nop 0
	global_load_lds_dwordx4 v134, s[18:19]
	s_mov_b32 m0, s31
	s_nop 0
	global_load_lds_dwordx4 v130, s[18:19]
	s_waitcnt vmcnt(8)
	s_waitcnt lgkmcnt(0)
	s_barrier
	s_setprio 1
	v_mfma_f32_16x16x32_bf16 v[60:63], v[140:143], v[214:217], 0
	v_mfma_f32_16x16x32_bf16 v[52:55], v[172:175], v[214:217], 0
	v_mfma_f32_16x16x32_bf16 v[44:47], v[140:143], v[222:225], 0
	v_mfma_f32_16x16x32_bf16 v[36:39], v[172:175], v[222:225], 0
	v_mfma_f32_16x16x32_bf16 v[28:31], v[140:143], v[230:233], 0
	v_mfma_f32_16x16x32_bf16 v[20:23], v[172:175], v[230:233], 0
	v_mfma_f32_16x16x32_bf16 v[12:15], v[140:143], v[238:241], 0
	v_mfma_f32_16x16x32_bf16 v[4:7], v[172:175], v[238:241], 0
	v_mfma_f32_16x16x32_bf16 v[60:63], v[168:171], v[218:221], v[60:63]
	v_mfma_f32_16x16x32_bf16 v[52:55], v[176:179], v[218:221], v[52:55]
	v_mfma_f32_16x16x32_bf16 v[44:47], v[168:171], v[226:229], v[44:47]
	v_mfma_f32_16x16x32_bf16 v[36:39], v[176:179], v[226:229], v[36:39]
	v_mfma_f32_16x16x32_bf16 v[28:31], v[168:171], v[234:237], v[28:31]
	v_mfma_f32_16x16x32_bf16 v[20:23], v[176:179], v[234:237], v[20:23]
	v_mfma_f32_16x16x32_bf16 v[12:15], v[168:171], v[242:245], v[12:15]
	v_mfma_f32_16x16x32_bf16 v[4:7], v[176:179], v[242:245], v[4:7]
	v_mfma_f32_16x16x32_bf16 v[56:59], v[180:183], v[214:217], 0
	v_mfma_f32_16x16x32_bf16 v[48:51], v[188:191], v[214:217], 0
	v_mfma_f32_16x16x32_bf16 v[40:43], v[180:183], v[222:225], 0
	v_mfma_f32_16x16x32_bf16 v[32:35], v[188:191], v[222:225], 0
	v_mfma_f32_16x16x32_bf16 v[24:27], v[180:183], v[230:233], 0
	v_mfma_f32_16x16x32_bf16 v[16:19], v[188:191], v[230:233], 0
	v_mfma_f32_16x16x32_bf16 v[8:11], v[180:183], v[238:241], 0
	v_mfma_f32_16x16x32_bf16 v[0:3], v[188:191], v[238:241], 0
	v_mfma_f32_16x16x32_bf16 v[56:59], v[184:187], v[218:221], v[56:59]
	v_mfma_f32_16x16x32_bf16 v[48:51], v[210:213], v[218:221], v[48:51]
	v_mfma_f32_16x16x32_bf16 v[40:43], v[184:187], v[226:229], v[40:43]
	v_mfma_f32_16x16x32_bf16 v[32:35], v[210:213], v[226:229], v[32:35]
	v_mfma_f32_16x16x32_bf16 v[24:27], v[184:187], v[234:237], v[24:27]
	v_mfma_f32_16x16x32_bf16 v[16:19], v[210:213], v[234:237], v[16:19]
	v_mfma_f32_16x16x32_bf16 v[8:11], v[184:187], v[242:245], v[8:11]
	v_mfma_f32_16x16x32_bf16 v[0:3], v[210:213], v[242:245], v[0:3]
	s_setprio 0
	s_barrier
; #define PG8_STAGE(bufoff, gbase, voff) do { _Pragma("unroll") for (int _i = 0; _i < 2; ++_i) \
;         __builtin_amdgcn_global_load_lds((const unsigned*)((const char*)(gbase) + (voff)[_i]), (PG8_LAS unsigned*)(lds + (bufoff) + ldsw + _i * 8192), 16, 0, 0); } while (0)
; #define PG8_LDA(dst, b, h) do { _Pragma("unroll") for (int m = 0; m < 4; ++m) _Pragma("unroll") for (int k = 0; k < 2; ++k) dst[m][k] = *(const PG8_LAS bf16x8*)(lds + PG8_SA(b, h) + aoff + m * 2048 + k * 1024); } while (0)
; #define PG8_LDB(dst, b, h) do { _Pragma("unroll") for (int n = 0; n < 2; ++n) _Pragma("unroll") for (int k = 0; k < 2; ++k) dst[n][k] = *(const PG8_LAS bf16x8*)(lds + PG8_SB(b, h) + boff + n * 2048 + k * 1024); } while (0)
; #define PG8_MMA(ai, bj, At, Bt) do { __builtin_amdgcn_s_setprio(1); _Pragma("unroll") for (int m = 0; m < 4; ++m) _Pragma("unroll") for (int n = 0; n < 2; ++n) _Pragma("unroll") for (int k = 0; k < 2; ++k) \
;         acc[ai][bj][m][n] = __builtin_amdgcn_mfma_f32_16x16x32_bf16(Bt[n][k], At[m][k], acc[ai][bj][m][n], 0, 0, 0); __builtin_amdgcn_s_setprio(0); } while (0)
; #define PG8_WAIT_V(n) asm volatile("s_waitcnt vmcnt(" #n ")" ::: "memory")
; #define PG8_WAIT_L(n) asm volatile("s_waitcnt lgkmcnt(" #n ")" ::: "memory")
; #define PG8_BAR __builtin_amdgcn_s_barrier()
; #define PG8_SCHED __builtin_amdgcn_sched_barrier(0)
; template <class Epi, class Sched, bool ALIGN_EPI = false, bool SP2 = false>
; __device__ __forceinline__ void gemm_phase(PG8_LAS unsigned char* lds, const Gemm g, const Sched& S, const Epi& E) {
;     ...
;         for (int t = 0; t < nt; t += 2) {
;     ...
;             PG8_LDB(B0, 1, 0); PG8_LDB(B1, 1, 1); PG8_SCHED; PG8_LDA(At, 1, 0); PG8_STAGE(PG8_SA(0, 1), a2 + hstep, voffA);
;             PG8_WAIT_V(8); PG8_WAIT_L(0); PG8_BAR; PG8_MMA(0, 0, At, B0); PG8_MMA(0, 1, At, B1); PG8_BAR; PG8_SCHED;
;             PG8_LDA(At, 1, 1); PG8_STAGE(PG8_SB(1, 0), b3, voffB); PG8_STAGE(PG8_SB(1, 1), b3 + hstep, voffB); PG8_STAGE(PG8_SA(1, 0), a3, voffA);
;             PG8_WAIT_V(8); PG8_WAIT_L(0); PG8_BAR; PG8_MMA(1, 0, At, B0); PG8_MMA(1, 1, At, B1); PG8_BAR; PG8_SCHED;
	ds_read_b128 v[140:143], v254 offset:32768
	ds_read_b128 v[168:171], v254 offset:33792
	ds_read_b128 v[172:175], v254 offset:34816
	ds_read_b128 v[176:179], v254 offset:35840
	ds_read_b128 v[180:183], v254 offset:49152
	ds_read_b128 v[184:187], v254 offset:50176
	ds_read_b128 v[188:191], v254 offset:51200
	ds_read_b128 v[210:213], v254 offset:52224
	s_add_u32 s18, s18, 0x40000
	s_addc_u32 s19, s19, 0
	s_mov_b32 m0, s33
	ds_read_b128 v[214:217], v165 offset:32768
	ds_read_b128 v[218:221], v165 offset:33792
	ds_read_b128 v[222:225], v165 offset:34816
	ds_read_b128 v[226:229], v165 offset:35840
	ds_read_b128 v[230:233], v165 offset:36864
	ds_read_b128 v[234:237], v165 offset:37888
	ds_read_b128 v[238:241], v165 offset:38912
	ds_read_b128 v[242:245], v165 offset:39936
	global_load_lds_dwordx4 v134, s[18:19]
	s_mov_b32 m0, s34
	s_nop 0
	global_load_lds_dwordx4 v130, s[18:19]
	s_waitcnt vmcnt(8)
	s_waitcnt lgkmcnt(0)
	s_barrier
	s_setprio 1
	v_mfma_f32_16x16x32_bf16 v[124:127], v[140:143], v[214:217], v[124:127]
	v_mfma_f32_16x16x32_bf16 v[116:119], v[172:175], v[214:217], v[116:119]
	v_mfma_f32_16x16x32_bf16 v[108:111], v[140:143], v[222:225], v[108:111]
	v_mfma_f32_16x16x32_bf16 v[100:103], v[172:175], v[222:225], v[100:103]
	v_mfma_f32_16x16x32_bf16 v[92:95], v[140:143], v[230:233], v[92:95]
	v_mfma_f32_16x16x32_bf16 v[84:87], v[172:175], v[230:233], v[84:87]
	v_mfma_f32_16x16x32_bf16 v[76:79], v[140:143], v[238:241], v[76:79]
	v_mfma_f32_16x16x32_bf16 v[68:71], v[172:175], v[238:241], v[68:71]
	v_mfma_f32_16x16x32_bf16 v[124:127], v[168:171], v[218:221], v[124:127]
	v_mfma_f32_16x16x32_bf16 v[116:119], v[176:179], v[218:221], v[116:119]
	v_mfma_f32_16x16x32_bf16 v[108:111], v[168:171], v[226:229], v[108:111]
	v_mfma_f32_16x16x32_bf16 v[100:103], v[176:179], v[226:229], v[100:103]
	v_mfma_f32_16x16x32_bf16 v[92:95], v[168:171], v[234:237], v[92:95]
	v_mfma_f32_16x16x32_bf16 v[84:87], v[176:179], v[234:237], v[84:87]
	v_mfma_f32_16x16x32_bf16 v[76:79], v[168:171], v[242:245], v[76:79]
	v_mfma_f32_16x16x32_bf16 v[68:71], v[176:179], v[242:245], v[68:71]
	v_mfma_f32_16x16x32_bf16 v[120:123], v[180:183], v[214:217], v[120:123]
	v_mfma_f32_16x16x32_bf16 v[112:115], v[188:191], v[214:217], v[112:115]
	v_mfma_f32_16x16x32_bf16 v[104:107], v[180:183], v[222:225], v[104:107]
	v_mfma_f32_16x16x32_bf16 v[96:99], v[188:191], v[222:225], v[96:99]
	v_mfma_f32_16x16x32_bf16 v[88:91], v[180:183], v[230:233], v[88:91]
	v_mfma_f32_16x16x32_bf16 v[80:83], v[188:191], v[230:233], v[80:83]
	v_mfma_f32_16x16x32_bf16 v[72:75], v[180:183], v[238:241], v[72:75]
	v_mfma_f32_16x16x32_bf16 v[64:67], v[188:191], v[238:241], v[64:67]
	v_mfma_f32_16x16x32_bf16 v[120:123], v[184:187], v[218:221], v[120:123]
	v_mfma_f32_16x16x32_bf16 v[112:115], v[210:213], v[218:221], v[112:115]
	v_mfma_f32_16x16x32_bf16 v[104:107], v[184:187], v[226:229], v[104:107]
	v_mfma_f32_16x16x32_bf16 v[96:99], v[210:213], v[226:229], v[96:99]
	v_mfma_f32_16x16x32_bf16 v[88:91], v[184:187], v[234:237], v[88:91]
	v_mfma_f32_16x16x32_bf16 v[80:83], v[210:213], v[234:237], v[80:83]
	v_mfma_f32_16x16x32_bf16 v[72:75], v[184:187], v[242:245], v[72:75]
	v_mfma_f32_16x16x32_bf16 v[64:67], v[210:213], v[242:245], v[64:67]
	s_setprio 0
	s_barrier
	s_mov_b32 m0, s37
	s_add_u32 s16, s16, 0x40080
	s_addc_u32 s17, s17, 0
	ds_read_b128 v[214:217], v165 offset:49152
	ds_read_b128 v[218:221], v165 offset:50176
	ds_read_b128 v[222:225], v165 offset:51200
	ds_read_b128 v[226:229], v165 offset:52224
	ds_read_b128 v[230:233], v165 offset:53248
	ds_read_b128 v[234:237], v165 offset:54272
	ds_read_b128 v[238:241], v165 offset:55296
	ds_read_b128 v[242:245], v165 offset:56320
	s_add_u32 s98, s16, 0xfffc0000
	s_addc_u32 s99, s17, -1
	global_load_lds_dwordx4 v132, s[98:99]
	s_mov_b32 m0, s38
	s_nop 0
	global_load_lds_dwordx4 v128, s[98:99]
	s_mov_b32 m0, s41
	s_nop 0
	global_load_lds_dwordx4 v132, s[16:17]
	s_mov_b32 m0, s42
	s_nop 0
	global_load_lds_dwordx4 v128, s[16:17]
	s_mov_b32 m0, s39
	s_nop 0
	s_add_u32 s100, s18, 0xfffc0080
	s_addc_u32 s101, s19, -1
	global_load_lds_dwordx4 v134, s[100:101]
	s_mov_b32 m0, s40
	s_nop 0
	global_load_lds_dwordx4 v130, s[100:101]
	s_waitcnt vmcnt(8)
	s_waitcnt lgkmcnt(0)
	s_barrier
	s_setprio 1
	v_mfma_f32_16x16x32_bf16 v[60:63], v[140:143], v[214:217], v[60:63]
	v_mfma_f32_16x16x32_bf16 v[52:55], v[172:175], v[214:217], v[52:55]
	v_mfma_f32_16x16x32_bf16 v[44:47], v[140:143], v[222:225], v[44:47]
	v_mfma_f32_16x16x32_bf16 v[36:39], v[172:175], v[222:225], v[36:39]
	v_mfma_f32_16x16x32_bf16 v[28:31], v[140:143], v[230:233], v[28:31]
	v_mfma_f32_16x16x32_bf16 v[20:23], v[172:175], v[230:233], v[20:23]
	v_mfma_f32_16x16x32_bf16 v[12:15], v[140:143], v[238:241], v[12:15]
	v_mfma_f32_16x16x32_bf16 v[4:7], v[172:175], v[238:241], v[4:7]
	v_mfma_f32_16x16x32_bf16 v[60:63], v[168:171], v[218:221], v[60:63]
	v_mfma_f32_16x16x32_bf16 v[52:55], v[176:179], v[218:221], v[52:55]
	v_mfma_f32_16x16x32_bf16 v[44:47], v[168:171], v[226:229], v[44:47]
	v_mfma_f32_16x16x32_bf16 v[36:39], v[176:179], v[226:229], v[36:39]
	v_mfma_f32_16x16x32_bf16 v[28:31], v[168:171], v[234:237], v[28:31]
	v_mfma_f32_16x16x32_bf16 v[20:23], v[176:179], v[234:237], v[20:23]
	v_mfma_f32_16x16x32_bf16 v[12:15], v[168:171], v[242:245], v[12:15]
	v_mfma_f32_16x16x32_bf16 v[4:7], v[176:179], v[242:245], v[4:7]
	v_mfma_f32_16x16x32_bf16 v[56:59], v[180:183], v[214:217], v[56:59]
	v_mfma_f32_16x16x32_bf16 v[48:51], v[188:191], v[214:217], v[48:51]
	v_mfma_f32_16x16x32_bf16 v[40:43], v[180:183], v[222:225], v[40:43]
	v_mfma_f32_16x16x32_bf16 v[32:35], v[188:191], v[222:225], v[32:35]
	v_mfma_f32_16x16x32_bf16 v[24:27], v[180:183], v[230:233], v[24:27]
	v_mfma_f32_16x16x32_bf16 v[16:19], v[188:191], v[230:233], v[16:19]
	v_mfma_f32_16x16x32_bf16 v[8:11], v[180:183], v[238:241], v[8:11]
	v_mfma_f32_16x16x32_bf16 v[0:3], v[188:191], v[238:241], v[0:3]
	v_mfma_f32_16x16x32_bf16 v[56:59], v[184:187], v[218:221], v[56:59]
	v_mfma_f32_16x16x32_bf16 v[48:51], v[210:213], v[218:221], v[48:51]
	v_mfma_f32_16x16x32_bf16 v[40:43], v[184:187], v[226:229], v[40:43]
	v_mfma_f32_16x16x32_bf16 v[32:35], v[210:213], v[226:229], v[32:35]
	v_mfma_f32_16x16x32_bf16 v[24:27], v[184:187], v[234:237], v[24:27]
	v_mfma_f32_16x16x32_bf16 v[16:19], v[210:213], v[234:237], v[16:19]
	v_mfma_f32_16x16x32_bf16 v[8:11], v[184:187], v[242:245], v[8:11]
	v_mfma_f32_16x16x32_bf16 v[0:3], v[210:213], v[242:245], v[0:3]
	s_setprio 0
	s_barrier
	s_add_i32 s53, s53, 2
	s_add_u32 s14, s14, 0x100
	s_addc_u32 s15, s15, 0
	s_add_u32 s51, s51, 0x100
	s_addc_u32 s52, s52, 0
	s_cmp_gt_u32 s53, 13
	s_cmp_eq_u32 s48, 0
	s_cbranch_scc1 .LBB0_446
; #define PG8_STAGE(bufoff, gbase, voff) do { _Pragma("unroll") for (int _i = 0; _i < 2; ++_i) \
;         __builtin_amdgcn_global_load_lds((const unsigned*)((const char*)(gbase) + (voff)[_i]), (PG8_LAS unsigned*)(lds + (bufoff) + ldsw + _i * 8192), 16, 0, 0); } while (0)
; #define PG8_LDA(dst, b, h) do { _Pragma("unroll") for (int m = 0; m < 4; ++m) _Pragma("unroll") for (int k = 0; k < 2; ++k) dst[m][k] = *(const PG8_LAS bf16x8*)(lds + PG8_SA(b, h) + aoff + m * 2048 + k * 1024); } while (0)
; #define PG8_LDB(dst, b, h) do { _Pragma("unroll") for (int n = 0; n < 2; ++n) _Pragma("unroll") for (int k = 0; k < 2; ++k) dst[n][k] = *(const PG8_LAS bf16x8*)(lds + PG8_SB(b, h) + boff + n * 2048 + k * 1024); } while (0)
; #define PG8_WAIT_V(n) asm volatile("s_waitcnt vmcnt(" #n ")" ::: "memory")
; #define PG8_WAIT_L(n) asm volatile("s_waitcnt lgkmcnt(" #n ")" ::: "memory")
; #define PG8_BAR __builtin_amdgcn_s_barrier()
;     __device__ __forceinline__ void operator()(const f32x4 (&acc)[2][2][4][2], const Unit& u, int ui, int wr, int wc, int fr, int fq) const {
;     ...
;                 __builtin_nontemporal_store(w, (u32x4*)(H + (size_t)row * ldh + col0)); }
; template <class Epi, class Sched, bool ALIGN_EPI = false, bool SP2 = false>
; __device__ __forceinline__ void gemm_phase(PG8_LAS unsigned char* lds, const Gemm g, const Sched& S, const Epi& E) {
;     ...
;             PG8_LDB(B0, 0, 0); PG8_LDB(B1, 0, 1); PG8_SCHED; PG8_LDA(At, 0, 0); PG8_STAGE(PG8_SA(1, 1), a1 + hstep, voffA);
;             PG8_WAIT_V(8); PG8_WAIT_L(0); PG8_BAR; PG8_MMA(0, 0, At, B0); PG8_MMA(0, 1, At, B1); PG8_BAR; PG8_SCHED;
;             PG8_LDA(At, 0, 1); PG8_STAGE(PG8_SB(0, 0), b2, voffB); PG8_STAGE(PG8_SB(0, 1), b2 + hstep, voffB); PG8_STAGE(PG8_SA(0, 0), a2, voffA);
;             PG8_WAIT_V(8); PG8_WAIT_L(0); PG8_BAR; PG8_MMA(1, 0, At, B0); PG8_MMA(1, 1, At, B1); PG8_BAR; PG8_SCHED;
;             PG8_LDB(B0, 1, 0); PG8_LDB(B1, 1, 1); PG8_SCHED; PG8_LDA(At, 1, 0); PG8_STAGE(PG8_SA(0, 1), a2 + hstep, voffA);
;             PG8_WAIT_V(8); PG8_WAIT_L(0); PG8_BAR; PG8_MMA(0, 0, At, B0); PG8_MMA(0, 1, At, B1); PG8_BAR; PG8_SCHED;
;             PG8_LDA(At, 1, 1); PG8_STAGE(PG8_SB(1, 0), b3, voffB); PG8_STAGE(PG8_SB(1, 1), b3 + hstep, voffB); PG8_STAGE(PG8_SA(1, 0), a3, voffA);
;             PG8_WAIT_V(8); PG8_WAIT_L(0); PG8_BAR; PG8_MMA(1, 0, At, B0); PG8_MMA(1, 1, At, B1); PG8_BAR; PG8_SCHED;
.Lup_sbody_0:
	ds_read_b128 v[140:143], v254
	ds_read_b128 v[168:171], v254 offset:1024
	ds_read_b128 v[172:175], v254 offset:2048
	ds_read_b128 v[176:179], v254 offset:3072
	ds_read_b128 v[180:183], v254 offset:16384
	ds_read_b128 v[184:187], v254 offset:17408
	ds_read_b128 v[188:191], v254 offset:18432
	ds_read_b128 v[210:213], v254 offset:19456
	s_add_u32 s16, s14, 0xfffc0080
	s_addc_u32 s17, s15, -1
	s_cmp_eq_u32 s53, 12
	s_cselect_b32 s19, s7, s17
	s_cselect_b32 s18, s49, s16
	s_cselect_b32 s17, s5, s52
	s_cselect_b32 s16, s50, s51
	s_mov_b32 m0, s43
	ds_read_b128 v[214:217], v165
	ds_read_b128 v[218:221], v165 offset:1024
	ds_read_b128 v[222:225], v165 offset:2048
	ds_read_b128 v[226:229], v165 offset:3072
	ds_read_b128 v[230:233], v165 offset:4096
	ds_read_b128 v[234:237], v165 offset:5120
	ds_read_b128 v[238:241], v165 offset:6144
	ds_read_b128 v[242:245], v165 offset:7168
	global_load_lds_dwordx4 v136, s[14:15]
	s_mov_b32 m0, s44
	s_nop 0
	global_load_lds_dwordx4 v138, s[14:15]
	s_waitcnt vmcnt(8)
	s_waitcnt lgkmcnt(0)
	s_barrier
	s_setprio 1
	v_mfma_f32_16x16x32_bf16 v[124:127], v[140:143], v[214:217], v[124:127]
	v_mfma_f32_16x16x32_bf16 v[116:119], v[172:175], v[214:217], v[116:119]
	v_mfma_f32_16x16x32_bf16 v[108:111], v[140:143], v[222:225], v[108:111]
	v_mfma_f32_16x16x32_bf16 v[100:103], v[172:175], v[222:225], v[100:103]
	v_mfma_f32_16x16x32_bf16 v[92:95], v[140:143], v[230:233], v[92:95]
	v_mfma_f32_16x16x32_bf16 v[84:87], v[172:175], v[230:233], v[84:87]
	v_mfma_f32_16x16x32_bf16 v[76:79], v[140:143], v[238:241], v[76:79]
	v_mfma_f32_16x16x32_bf16 v[68:71], v[172:175], v[238:241], v[68:71]
	v_mfma_f32_16x16x32_bf16 v[124:127], v[168:171], v[218:221], v[124:127]
	v_mfma_f32_16x16x32_bf16 v[116:119], v[176:179], v[218:221], v[116:119]
	v_mfma_f32_16x16x32_bf16 v[108:111], v[168:171], v[226:229], v[108:111]
	v_mfma_f32_16x16x32_bf16 v[100:103], v[176:179], v[226:229], v[100:103]
	v_mfma_f32_16x16x32_bf16 v[92:95], v[168:171], v[234:237], v[92:95]
	v_mfma_f32_16x16x32_bf16 v[84:87], v[176:179], v[234:237], v[84:87]
	v_mfma_f32_16x16x32_bf16 v[76:79], v[168:171], v[242:245], v[76:79]
	v_mfma_f32_16x16x32_bf16 v[68:71], v[176:179], v[242:245], v[68:71]
	v_mfma_f32_16x16x32_bf16 v[120:123], v[180:183], v[214:217], v[120:123]
	v_mfma_f32_16x16x32_bf16 v[112:115], v[188:191], v[214:217], v[112:115]
	v_mfma_f32_16x16x32_bf16 v[104:107], v[180:183], v[222:225], v[104:107]
	v_mfma_f32_16x16x32_bf16 v[96:99], v[188:191], v[222:225], v[96:99]
	v_mfma_f32_16x16x32_bf16 v[88:91], v[180:183], v[230:233], v[88:91]
	v_mfma_f32_16x16x32_bf16 v[80:83], v[188:191], v[230:233], v[80:83]
	v_mfma_f32_16x16x32_bf16 v[72:75], v[180:183], v[238:241], v[72:75]
	v_mfma_f32_16x16x32_bf16 v[64:67], v[188:191], v[238:241], v[64:67]
	v_mfma_f32_16x16x32_bf16 v[120:123], v[184:187], v[218:221], v[120:123]
	v_mfma_f32_16x16x32_bf16 v[112:115], v[210:213], v[218:221], v[112:115]
	v_mfma_f32_16x16x32_bf16 v[104:107], v[184:187], v[226:229], v[104:107]
	v_mfma_f32_16x16x32_bf16 v[96:99], v[210:213], v[226:229], v[96:99]
	v_mfma_f32_16x16x32_bf16 v[88:91], v[184:187], v[234:237], v[88:91]
	v_mfma_f32_16x16x32_bf16 v[80:83], v[210:213], v[234:237], v[80:83]
	v_mfma_f32_16x16x32_bf16 v[72:75], v[184:187], v[242:245], v[72:75]
	v_mfma_f32_16x16x32_bf16 v[64:67], v[210:213], v[242:245], v[64:67]
	s_setprio 0
	s_barrier
	s_mov_b32 m0, s27
	s_add_u32 s54, s16, 0x40000
	s_addc_u32 s55, s17, 0
	ds_read_b128 v[214:217], v165 offset:16384
	ds_read_b128 v[218:221], v165 offset:17408
	ds_read_b128 v[222:225], v165 offset:18432
	ds_read_b128 v[226:229], v165 offset:19456
	ds_read_b128 v[230:233], v165 offset:20480
	ds_read_b128 v[234:237], v165 offset:21504
	ds_read_b128 v[238:241], v165 offset:22528
	ds_read_b128 v[242:245], v165 offset:23552
	global_load_lds_dwordx4 v132, s[16:17]
	s_mov_b32 m0, s28
	s_nop 0
	global_load_lds_dwordx4 v128, s[16:17]
	s_mov_b32 m0, s29
	s_nop 0
	global_load_lds_dwordx4 v132, s[54:55]
	s_mov_b32 m0, s30
	s_nop 0
	global_load_lds_dwordx4 v128, s[54:55]
	s_mov_b32 m0, s22
	s_nop 0
	global_load_lds_dwordx4 v134, s[18:19]
	s_mov_b32 m0, s31
	s_nop 0
	global_load_lds_dwordx4 v130, s[18:19]
	s_add_u32 s100, s20, 0xb0000
	s_addc_u32 s101, s21, 0
	global_store_dwordx4 v255, v[150:153], s[100:101] nt
	s_waitcnt vmcnt(9)
	s_waitcnt lgkmcnt(0)
	s_barrier
	s_setprio 1
	v_mfma_f32_16x16x32_bf16 v[60:63], v[140:143], v[214:217], v[60:63]
	v_mfma_f32_16x16x32_bf16 v[52:55], v[172:175], v[214:217], v[52:55]
	v_mfma_f32_16x16x32_bf16 v[44:47], v[140:143], v[222:225], v[44:47]
	v_mfma_f32_16x16x32_bf16 v[36:39], v[172:175], v[222:225], v[36:39]
	v_mfma_f32_16x16x32_bf16 v[28:31], v[140:143], v[230:233], v[28:31]
	v_mfma_f32_16x16x32_bf16 v[20:23], v[172:175], v[230:233], v[20:23]
	v_mfma_f32_16x16x32_bf16 v[12:15], v[140:143], v[238:241], v[12:15]
	v_mfma_f32_16x16x32_bf16 v[4:7], v[172:175], v[238:241], v[4:7]
	v_mfma_f32_16x16x32_bf16 v[60:63], v[168:171], v[218:221], v[60:63]
	v_mfma_f32_16x16x32_bf16 v[52:55], v[176:179], v[218:221], v[52:55]
	v_mfma_f32_16x16x32_bf16 v[44:47], v[168:171], v[226:229], v[44:47]
	v_mfma_f32_16x16x32_bf16 v[36:39], v[176:179], v[226:229], v[36:39]
	v_mfma_f32_16x16x32_bf16 v[28:31], v[168:171], v[234:237], v[28:31]
	v_mfma_f32_16x16x32_bf16 v[20:23], v[176:179], v[234:237], v[20:23]
	v_mfma_f32_16x16x32_bf16 v[12:15], v[168:171], v[242:245], v[12:15]
	v_mfma_f32_16x16x32_bf16 v[4:7], v[176:179], v[242:245], v[4:7]
	v_mfma_f32_16x16x32_bf16 v[56:59], v[180:183], v[214:217], v[56:59]
	v_mfma_f32_16x16x32_bf16 v[48:51], v[188:191], v[214:217], v[48:51]
	v_mfma_f32_16x16x32_bf16 v[40:43], v[180:183], v[222:225], v[40:43]
	v_mfma_f32_16x16x32_bf16 v[32:35], v[188:191], v[222:225], v[32:35]
	v_mfma_f32_16x16x32_bf16 v[24:27], v[180:183], v[230:233], v[24:27]
	v_mfma_f32_16x16x32_bf16 v[16:19], v[188:191], v[230:233], v[16:19]
	v_mfma_f32_16x16x32_bf16 v[8:11], v[180:183], v[238:241], v[8:11]
	v_mfma_f32_16x16x32_bf16 v[0:3], v[188:191], v[238:241], v[0:3]
	v_mfma_f32_16x16x32_bf16 v[56:59], v[184:187], v[218:221], v[56:59]
	v_mfma_f32_16x16x32_bf16 v[48:51], v[210:213], v[218:221], v[48:51]
	v_mfma_f32_16x16x32_bf16 v[40:43], v[184:187], v[226:229], v[40:43]
	v_mfma_f32_16x16x32_bf16 v[32:35], v[210:213], v[226:229], v[32:35]
	v_mfma_f32_16x16x32_bf16 v[24:27], v[184:187], v[234:237], v[24:27]
	v_mfma_f32_16x16x32_bf16 v[16:19], v[210:213], v[234:237], v[16:19]
	v_mfma_f32_16x16x32_bf16 v[8:11], v[184:187], v[242:245], v[8:11]
	v_mfma_f32_16x16x32_bf16 v[0:3], v[210:213], v[242:245], v[0:3]
	s_setprio 0
	s_barrier
; #define PG8_STAGE(bufoff, gbase, voff) do { _Pragma("unroll") for (int _i = 0; _i < 2; ++_i) \
;         __builtin_amdgcn_global_load_lds((const unsigned*)((const char*)(gbase) + (voff)[_i]), (PG8_LAS unsigned*)(lds + (bufoff) + ldsw + _i * 8192), 16, 0, 0); } while (0)
; #define PG8_LDA(dst, b, h) do { _Pragma("unroll") for (int m = 0; m < 4; ++m) _Pragma("unroll") for (int k = 0; k < 2; ++k) dst[m][k] = *(const PG8_LAS bf16x8*)(lds + PG8_SA(b, h) + aoff + m * 2048 + k * 1024); } while (0)
; #define PG8_LDB(dst, b, h) do { _Pragma("unroll") for (int n = 0; n < 2; ++n) _Pragma("unroll") for (int k = 0; k < 2; ++k) dst[n][k] = *(const PG8_LAS bf16x8*)(lds + PG8_SB(b, h) + boff + n * 2048 + k * 1024); } while (0)
; #define PG8_MMA(ai, bj, At, Bt) do { __builtin_amdgcn_s_setprio(1); _Pragma("unroll") for (int m = 0; m < 4; ++m) _Pragma("unroll") for (int n = 0; n < 2; ++n) _Pragma("unroll") for (int k = 0; k < 2; ++k) \
;         acc[ai][bj][m][n] = __builtin_amdgcn_mfma_f32_16x16x32_bf16(Bt[n][k], At[m][k], acc[ai][bj][m][n], 0, 0, 0); __builtin_amdgcn_s_setprio(0); } while (0)
; #define PG8_WAIT_V(n) asm volatile("s_waitcnt vmcnt(" #n ")" ::: "memory")
; #define PG8_WAIT_L(n) asm volatile("s_waitcnt lgkmcnt(" #n ")" ::: "memory")
; #define PG8_BAR __builtin_amdgcn_s_barrier()
; #define PG8_SCHED __builtin_amdgcn_sched_barrier(0)
; template <class Epi, class Sched, bool ALIGN_EPI = false, bool SP2 = false>
; __device__ __forceinline__ void gemm_phase(PG8_LAS unsigned char* lds, const Gemm g, const Sched& S, const Epi& E) {
;     ...
;             PG8_LDB(B0, 1, 0); PG8_LDB(B1, 1, 1); PG8_SCHED; PG8_LDA(At, 1, 0); PG8_STAGE(PG8_SA(0, 1), a2 + hstep, voffA);
;             PG8_WAIT_V(8); PG8_WAIT_L(0); PG8_BAR; PG8_MMA(0, 0, At, B0); PG8_MMA(0, 1, At, B1); PG8_BAR; PG8_SCHED;
;             PG8_LDA(At, 1, 1); PG8_STAGE(PG8_SB(1, 0), b3, voffB); PG8_STAGE(PG8_SB(1, 1), b3 + hstep, voffB); PG8_STAGE(PG8_SA(1, 0), a3, voffA);
;             PG8_WAIT_V(8); PG8_WAIT_L(0); PG8_BAR; PG8_MMA(1, 0, At, B0); PG8_MMA(1, 1, At, B1); PG8_BAR; PG8_SCHED;
	ds_read_b128 v[140:143], v254 offset:32768
	ds_read_b128 v[168:171], v254 offset:33792
	ds_read_b128 v[172:175], v254 offset:34816
	ds_read_b128 v[176:179], v254 offset:35840
	ds_read_b128 v[180:183], v254 offset:49152
	ds_read_b128 v[184:187], v254 offset:50176
	ds_read_b128 v[188:191], v254 offset:51200
	ds_read_b128 v[210:213], v254 offset:52224
	s_add_u32 s18, s18, 0x40000
	s_addc_u32 s19, s19, 0
	s_mov_b32 m0, s33
	ds_read_b128 v[214:217], v165 offset:32768
	ds_read_b128 v[218:221], v165 offset:33792
	ds_read_b128 v[222:225], v165 offset:34816
	ds_read_b128 v[226:229], v165 offset:35840
	ds_read_b128 v[230:233], v165 offset:36864
	ds_read_b128 v[234:237], v165 offset:37888
	ds_read_b128 v[238:241], v165 offset:38912
	ds_read_b128 v[242:245], v165 offset:39936
	global_load_lds_dwordx4 v134, s[18:19]
	s_mov_b32 m0, s34
	s_nop 0
	global_load_lds_dwordx4 v130, s[18:19]
	s_waitcnt vmcnt(9)
	s_waitcnt lgkmcnt(0)
	s_barrier
	s_setprio 1
	v_mfma_f32_16x16x32_bf16 v[124:127], v[140:143], v[214:217], v[124:127]
	v_mfma_f32_16x16x32_bf16 v[116:119], v[172:175], v[214:217], v[116:119]
	v_mfma_f32_16x16x32_bf16 v[108:111], v[140:143], v[222:225], v[108:111]
	v_mfma_f32_16x16x32_bf16 v[100:103], v[172:175], v[222:225], v[100:103]
	v_mfma_f32_16x16x32_bf16 v[92:95], v[140:143], v[230:233], v[92:95]
	v_mfma_f32_16x16x32_bf16 v[84:87], v[172:175], v[230:233], v[84:87]
	v_mfma_f32_16x16x32_bf16 v[76:79], v[140:143], v[238:241], v[76:79]
	v_mfma_f32_16x16x32_bf16 v[68:71], v[172:175], v[238:241], v[68:71]
	v_mfma_f32_16x16x32_bf16 v[124:127], v[168:171], v[218:221], v[124:127]
	v_mfma_f32_16x16x32_bf16 v[116:119], v[176:179], v[218:221], v[116:119]
	v_mfma_f32_16x16x32_bf16 v[108:111], v[168:171], v[226:229], v[108:111]
	v_mfma_f32_16x16x32_bf16 v[100:103], v[176:179], v[226:229], v[100:103]
	v_mfma_f32_16x16x32_bf16 v[92:95], v[168:171], v[234:237], v[92:95]
	v_mfma_f32_16x16x32_bf16 v[84:87], v[176:179], v[234:237], v[84:87]
	v_mfma_f32_16x16x32_bf16 v[76:79], v[168:171], v[242:245], v[76:79]
	v_mfma_f32_16x16x32_bf16 v[68:71], v[176:179], v[242:245], v[68:71]
	v_mfma_f32_16x16x32_bf16 v[120:123], v[180:183], v[214:217], v[120:123]
	v_mfma_f32_16x16x32_bf16 v[112:115], v[188:191], v[214:217], v[112:115]
	v_mfma_f32_16x16x32_bf16 v[104:107], v[180:183], v[222:225], v[104:107]
	v_mfma_f32_16x16x32_bf16 v[96:99], v[188:191], v[222:225], v[96:99]
	v_mfma_f32_16x16x32_bf16 v[88:91], v[180:183], v[230:233], v[88:91]
	v_mfma_f32_16x16x32_bf16 v[80:83], v[188:191], v[230:233], v[80:83]
	v_mfma_f32_16x16x32_bf16 v[72:75], v[180:183], v[238:241], v[72:75]
	v_mfma_f32_16x16x32_bf16 v[64:67], v[188:191], v[238:241], v[64:67]
	v_mfma_f32_16x16x32_bf16 v[120:123], v[184:187], v[218:221], v[120:123]
	v_mfma_f32_16x16x32_bf16 v[112:115], v[210:213], v[218:221], v[112:115]
	v_mfma_f32_16x16x32_bf16 v[104:107], v[184:187], v[226:229], v[104:107]
	v_mfma_f32_16x16x32_bf16 v[96:99], v[210:213], v[226:229], v[96:99]
	v_mfma_f32_16x16x32_bf16 v[88:91], v[184:187], v[234:237], v[88:91]
	v_mfma_f32_16x16x32_bf16 v[80:83], v[210:213], v[234:237], v[80:83]
	v_mfma_f32_16x16x32_bf16 v[72:75], v[184:187], v[242:245], v[72:75]
	v_mfma_f32_16x16x32_bf16 v[64:67], v[210:213], v[242:245], v[64:67]
	s_setprio 0
	s_barrier
	s_mov_b32 m0, s37
	s_add_u32 s16, s16, 0x40080
	s_addc_u32 s17, s17, 0
	ds_read_b128 v[214:217], v165 offset:49152
	ds_read_b128 v[218:221], v165 offset:50176
	ds_read_b128 v[222:225], v165 offset:51200
	ds_read_b128 v[226:229], v165 offset:52224
	ds_read_b128 v[230:233], v165 offset:53248
	ds_read_b128 v[234:237], v165 offset:54272
	ds_read_b128 v[238:241], v165 offset:55296
	ds_read_b128 v[242:245], v165 offset:56320
	s_add_u32 s98, s16, 0xfffc0000
	s_addc_u32 s99, s17, -1
	global_load_lds_dwordx4 v132, s[98:99]
	s_mov_b32 m0, s38
	s_nop 0
	global_load_lds_dwordx4 v128, s[98:99]
	s_mov_b32 m0, s41
	s_nop 0
	global_load_lds_dwordx4 v132, s[16:17]
	s_mov_b32 m0, s42
	s_nop 0
	global_load_lds_dwordx4 v128, s[16:17]
	s_mov_b32 m0, s39
	s_nop 0
	s_add_u32 s100, s18, 0xfffc0080
	s_addc_u32 s101, s19, -1
	global_load_lds_dwordx4 v134, s[100:101]
	s_mov_b32 m0, s40
	s_nop 0
	global_load_lds_dwordx4 v130, s[100:101]
	s_waitcnt vmcnt(9)
	s_waitcnt lgkmcnt(0)
	s_barrier
	s_setprio 1
	v_mfma_f32_16x16x32_bf16 v[60:63], v[140:143], v[214:217], v[60:63]
	v_mfma_f32_16x16x32_bf16 v[52:55], v[172:175], v[214:217], v[52:55]
	v_mfma_f32_16x16x32_bf16 v[44:47], v[140:143], v[222:225], v[44:47]
	v_mfma_f32_16x16x32_bf16 v[36:39], v[172:175], v[222:225], v[36:39]
	v_mfma_f32_16x16x32_bf16 v[28:31], v[140:143], v[230:233], v[28:31]
	v_mfma_f32_16x16x32_bf16 v[20:23], v[172:175], v[230:233], v[20:23]
	v_mfma_f32_16x16x32_bf16 v[12:15], v[140:143], v[238:241], v[12:15]
	v_mfma_f32_16x16x32_bf16 v[4:7], v[172:175], v[238:241], v[4:7]
	v_mfma_f32_16x16x32_bf16 v[60:63], v[168:171], v[218:221], v[60:63]
	v_mfma_f32_16x16x32_bf16 v[52:55], v[176:179], v[218:221], v[52:55]
	v_mfma_f32_16x16x32_bf16 v[44:47], v[168:171], v[226:229], v[44:47]
	v_mfma_f32_16x16x32_bf16 v[36:39], v[176:179], v[226:229], v[36:39]
	v_mfma_f32_16x16x32_bf16 v[28:31], v[168:171], v[234:237], v[28:31]
	v_mfma_f32_16x16x32_bf16 v[20:23], v[176:179], v[234:237], v[20:23]
	v_mfma_f32_16x16x32_bf16 v[12:15], v[168:171], v[242:245], v[12:15]
	v_mfma_f32_16x16x32_bf16 v[4:7], v[176:179], v[242:245], v[4:7]
	v_mfma_f32_16x16x32_bf16 v[56:59], v[180:183], v[214:217], v[56:59]
	v_mfma_f32_16x16x32_bf16 v[48:51], v[188:191], v[214:217], v[48:51]
	v_mfma_f32_16x16x32_bf16 v[40:43], v[180:183], v[222:225], v[40:43]
	v_mfma_f32_16x16x32_bf16 v[32:35], v[188:191], v[222:225], v[32:35]
	v_mfma_f32_16x16x32_bf16 v[24:27], v[180:183], v[230:233], v[24:27]
	v_mfma_f32_16x16x32_bf16 v[16:19], v[188:191], v[230:233], v[16:19]
	v_mfma_f32_16x16x32_bf16 v[8:11], v[180:183], v[238:241], v[8:11]
	v_mfma_f32_16x16x32_bf16 v[0:3], v[188:191], v[238:241], v[0:3]
	v_mfma_f32_16x16x32_bf16 v[56:59], v[184:187], v[218:221], v[56:59]
	v_mfma_f32_16x16x32_bf16 v[48:51], v[210:213], v[218:221], v[48:51]
	v_mfma_f32_16x16x32_bf16 v[40:43], v[184:187], v[226:229], v[40:43]
	v_mfma_f32_16x16x32_bf16 v[32:35], v[210:213], v[226:229], v[32:35]
	v_mfma_f32_16x16x32_bf16 v[24:27], v[184:187], v[234:237], v[24:27]
	v_mfma_f32_16x16x32_bf16 v[16:19], v[210:213], v[234:237], v[16:19]
	v_mfma_f32_16x16x32_bf16 v[8:11], v[184:187], v[242:245], v[8:11]
	v_mfma_f32_16x16x32_bf16 v[0:3], v[210:213], v[242:245], v[0:3]
	s_setprio 0
	s_barrier
	s_add_i32 s53, s53, 2
	s_add_u32 s14, s14, 0x100
	s_addc_u32 s15, s15, 0
	s_add_u32 s51, s51, 0x100
	s_addc_u32 s52, s52, 0
; #define PG8_STAGE(bufoff, gbase, voff) do { _Pragma("unroll") for (int _i = 0; _i < 2; ++_i) \
;         __builtin_amdgcn_global_load_lds((const unsigned*)((const char*)(gbase) + (voff)[_i]), (PG8_LAS unsigned*)(lds + (bufoff) + ldsw + _i * 8192), 16, 0, 0); } while (0)
; #define PG8_LDA(dst, b, h) do { _Pragma("unroll") for (int m = 0; m < 4; ++m) _Pragma("unroll") for (int k = 0; k < 2; ++k) dst[m][k] = *(const PG8_LAS bf16x8*)(lds + PG8_SA(b, h) + aoff + m * 2048 + k * 1024); } while (0)
; #define PG8_LDB(dst, b, h) do { _Pragma("unroll") for (int n = 0; n < 2; ++n) _Pragma("unroll") for (int k = 0; k < 2; ++k) dst[n][k] = *(const PG8_LAS bf16x8*)(lds + PG8_SB(b, h) + boff + n * 2048 + k * 1024); } while (0)
; #define PG8_WAIT_V(n) asm volatile("s_waitcnt vmcnt(" #n ")" ::: "memory")
; #define PG8_WAIT_L(n) asm volatile("s_waitcnt lgkmcnt(" #n ")" ::: "memory")
; #define PG8_BAR __builtin_amdgcn_s_barrier()
;     __device__ __forceinline__ void operator()(const f32x4 (&acc)[2][2][4][2], const Unit& u, int ui, int wr, int wc, int fr, int fq) const {
;     ...
;                 __builtin_nontemporal_store(w, (u32x4*)(H + (size_t)row * ldh + col0)); }
; template <class Epi, class Sched, bool ALIGN_EPI = false, bool SP2 = false>
; __device__ __forceinline__ void gemm_phase(PG8_LAS unsigned char* lds, const Gemm g, const Sched& S, const Epi& E) {
;     ...
;             PG8_LDB(B0, 0, 0); PG8_LDB(B1, 0, 1); PG8_SCHED; PG8_LDA(At, 0, 0); PG8_STAGE(PG8_SA(1, 1), a1 + hstep, voffA);
;             PG8_WAIT_V(8); PG8_WAIT_L(0); PG8_BAR; PG8_MMA(0, 0, At, B0); PG8_MMA(0, 1, At, B1); PG8_BAR; PG8_SCHED;
;             PG8_LDA(At, 0, 1); PG8_STAGE(PG8_SB(0, 0), b2, voffB); PG8_STAGE(PG8_SB(0, 1), b2 + hstep, voffB); PG8_STAGE(PG8_SA(0, 0), a2, voffA);
;             PG8_WAIT_V(8); PG8_WAIT_L(0); PG8_BAR; PG8_MMA(1, 0, At, B0); PG8_MMA(1, 1, At, B1); PG8_BAR; PG8_SCHED;
;             PG8_LDB(B0, 1, 0); PG8_LDB(B1, 1, 1); PG8_SCHED; PG8_LDA(At, 1, 0); PG8_STAGE(PG8_SA(0, 1), a2 + hstep, voffA);
;             PG8_WAIT_V(8); PG8_WAIT_L(0); PG8_BAR; PG8_MMA(0, 0, At, B0); PG8_MMA(0, 1, At, B1); PG8_BAR; PG8_SCHED;
;             PG8_LDA(At, 1, 1); PG8_STAGE(PG8_SB(1, 0), b3, voffB); PG8_STAGE(PG8_SB(1, 1), b3 + hstep, voffB); PG8_STAGE(PG8_SA(1, 0), a3, voffA);
;             PG8_WAIT_V(8); PG8_WAIT_L(0); PG8_BAR; PG8_MMA(1, 0, At, B0); PG8_MMA(1, 1, At, B1); PG8_BAR; PG8_SCHED;
.Lup_sbody_1:
	ds_read_b128 v[140:143], v254
	ds_read_b128 v[168:171], v254 offset:1024
	ds_read_b128 v[172:175], v254 offset:2048
	ds_read_b128 v[176:179], v254 offset:3072
	ds_read_b128 v[180:183], v254 offset:16384
	ds_read_b128 v[184:187], v254 offset:17408
	ds_read_b128 v[188:191], v254 offset:18432
	ds_read_b128 v[210:213], v254 offset:19456
	s_add_u32 s16, s14, 0xfffc0080
	s_addc_u32 s17, s15, -1
	s_cmp_eq_u32 s53, 12
	s_cselect_b32 s19, s7, s17
	s_cselect_b32 s18, s49, s16
	s_cselect_b32 s17, s5, s52
	s_cselect_b32 s16, s50, s51
	s_mov_b32 m0, s43
	ds_read_b128 v[214:217], v165
	ds_read_b128 v[218:221], v165 offset:1024
	ds_read_b128 v[222:225], v165 offset:2048
	ds_read_b128 v[226:229], v165 offset:3072
	ds_read_b128 v[230:233], v165 offset:4096
	ds_read_b128 v[234:237], v165 offset:5120
	ds_read_b128 v[238:241], v165 offset:6144
	ds_read_b128 v[242:245], v165 offset:7168
	global_load_lds_dwordx4 v136, s[14:15]
	s_mov_b32 m0, s44
	s_nop 0
	global_load_lds_dwordx4 v138, s[14:15]
	s_waitcnt vmcnt(8)
	s_waitcnt lgkmcnt(0)
	s_barrier
	s_setprio 1
	v_mfma_f32_16x16x32_bf16 v[124:127], v[140:143], v[214:217], v[124:127]
	v_mfma_f32_16x16x32_bf16 v[116:119], v[172:175], v[214:217], v[116:119]
	v_mfma_f32_16x16x32_bf16 v[108:111], v[140:143], v[222:225], v[108:111]
	v_mfma_f32_16x16x32_bf16 v[100:103], v[172:175], v[222:225], v[100:103]
	v_mfma_f32_16x16x32_bf16 v[92:95], v[140:143], v[230:233], v[92:95]
	v_mfma_f32_16x16x32_bf16 v[84:87], v[172:175], v[230:233], v[84:87]
	v_mfma_f32_16x16x32_bf16 v[76:79], v[140:143], v[238:241], v[76:79]
	v_mfma_f32_16x16x32_bf16 v[68:71], v[172:175], v[238:241], v[68:71]
	v_mfma_f32_16x16x32_bf16 v[124:127], v[168:171], v[218:221], v[124:127]
	v_mfma_f32_16x16x32_bf16 v[116:119], v[176:179], v[218:221], v[116:119]
	v_mfma_f32_16x16x32_bf16 v[108:111], v[168:171], v[226:229], v[108:111]
	v_mfma_f32_16x16x32_bf16 v[100:103], v[176:179], v[226:229], v[100:103]
	v_mfma_f32_16x16x32_bf16 v[92:95], v[168:171], v[234:237], v[92:95]
	v_mfma_f32_16x16x32_bf16 v[84:87], v[176:179], v[234:237], v[84:87]
	v_mfma_f32_16x16x32_bf16 v[76:79], v[168:171], v[242:245], v[76:79]
	v_mfma_f32_16x16x32_bf16 v[68:71], v[176:179], v[242:245], v[68:71]
	v_mfma_f32_16x16x32_bf16 v[120:123], v[180:183], v[214:217], v[120:123]
	v_mfma_f32_16x16x32_bf16 v[112:115], v[188:191], v[214:217], v[112:115]
	v_mfma_f32_16x16x32_bf16 v[104:107], v[180:183], v[222:225], v[104:107]
	v_mfma_f32_16x16x32_bf16 v[96:99], v[188:191], v[222:225], v[96:99]
	v_mfma_f32_16x16x32_bf16 v[88:91], v[180:183], v[230:233], v[88:91]
	v_mfma_f32_16x16x32_bf16 v[80:83], v[188:191], v[230:233], v[80:83]
	v_mfma_f32_16x16x32_bf16 v[72:75], v[180:183], v[238:241], v[72:75]
	v_mfma_f32_16x16x32_bf16 v[64:67], v[188:191], v[238:241], v[64:67]
	v_mfma_f32_16x16x32_bf16 v[120:123], v[184:187], v[218:221], v[120:123]
	v_mfma_f32_16x16x32_bf16 v[112:115], v[210:213], v[218:221], v[112:115]
	v_mfma_f32_16x16x32_bf16 v[104:107], v[184:187], v[226:229], v[104:107]
	v_mfma_f32_16x16x32_bf16 v[96:99], v[210:213], v[226:229], v[96:99]
	v_mfma_f32_16x16x32_bf16 v[88:91], v[184:187], v[234:237], v[88:91]
	v_mfma_f32_16x16x32_bf16 v[80:83], v[210:213], v[234:237], v[80:83]
	v_mfma_f32_16x16x32_bf16 v[72:75], v[184:187], v[242:245], v[72:75]
	v_mfma_f32_16x16x32_bf16 v[64:67], v[210:213], v[242:245], v[64:67]
	s_setprio 0
	s_barrier
	s_mov_b32 m0, s27
	s_add_u32 s54, s16, 0x40000
	s_addc_u32 s55, s17, 0
	ds_read_b128 v[214:217], v165 offset:16384
	ds_read_b128 v[218:221], v165 offset:17408
	ds_read_b128 v[222:225], v165 offset:18432
	ds_read_b128 v[226:229], v165 offset:19456
	ds_read_b128 v[230:233], v165 offset:20480
	ds_read_b128 v[234:237], v165 offset:21504
	ds_read_b128 v[238:241], v165 offset:22528
	ds_read_b128 v[242:245], v165 offset:23552
	global_load_lds_dwordx4 v132, s[16:17]
	s_mov_b32 m0, s28
	s_nop 0
	global_load_lds_dwordx4 v128, s[16:17]
	s_mov_b32 m0, s29
	s_nop 0
	global_load_lds_dwordx4 v132, s[54:55]
	s_mov_b32 m0, s30
	s_nop 0
	global_load_lds_dwordx4 v128, s[54:55]
	s_mov_b32 m0, s22
	s_nop 0
	global_load_lds_dwordx4 v134, s[18:19]
	s_mov_b32 m0, s31
	s_nop 0
	global_load_lds_dwordx4 v130, s[18:19]
	s_add_u32 s100, s20, 0xc6000
	s_addc_u32 s101, s21, 0
	global_store_dwordx4 v255, v[154:157], s[100:101] nt
	s_waitcnt vmcnt(9)
	s_waitcnt lgkmcnt(0)
	s_barrier
	s_setprio 1
	v_mfma_f32_16x16x32_bf16 v[60:63], v[140:143], v[214:217], v[60:63]
	v_mfma_f32_16x16x32_bf16 v[52:55], v[172:175], v[214:217], v[52:55]
	v_mfma_f32_16x16x32_bf16 v[44:47], v[140:143], v[222:225], v[44:47]
	v_mfma_f32_16x16x32_bf16 v[36:39], v[172:175], v[222:225], v[36:39]
	v_mfma_f32_16x16x32_bf16 v[28:31], v[140:143], v[230:233], v[28:31]
	v_mfma_f32_16x16x32_bf16 v[20:23], v[172:175], v[230:233], v[20:23]
	v_mfma_f32_16x16x32_bf16 v[12:15], v[140:143], v[238:241], v[12:15]
	v_mfma_f32_16x16x32_bf16 v[4:7], v[172:175], v[238:241], v[4:7]
	v_mfma_f32_16x16x32_bf16 v[60:63], v[168:171], v[218:221], v[60:63]
	v_mfma_f32_16x16x32_bf16 v[52:55], v[176:179], v[218:221], v[52:55]
	v_mfma_f32_16x16x32_bf16 v[44:47], v[168:171], v[226:229], v[44:47]
	v_mfma_f32_16x16x32_bf16 v[36:39], v[176:179], v[226:229], v[36:39]
	v_mfma_f32_16x16x32_bf16 v[28:31], v[168:171], v[234:237], v[28:31]
	v_mfma_f32_16x16x32_bf16 v[20:23], v[176:179], v[234:237], v[20:23]
	v_mfma_f32_16x16x32_bf16 v[12:15], v[168:171], v[242:245], v[12:15]
	v_mfma_f32_16x16x32_bf16 v[4:7], v[176:179], v[242:245], v[4:7]
	v_mfma_f32_16x16x32_bf16 v[56:59], v[180:183], v[214:217], v[56:59]
	v_mfma_f32_16x16x32_bf16 v[48:51], v[188:191], v[214:217], v[48:51]
	v_mfma_f32_16x16x32_bf16 v[40:43], v[180:183], v[222:225], v[40:43]
	v_mfma_f32_16x16x32_bf16 v[32:35], v[188:191], v[222:225], v[32:35]
	v_mfma_f32_16x16x32_bf16 v[24:27], v[180:183], v[230:233], v[24:27]
	v_mfma_f32_16x16x32_bf16 v[16:19], v[188:191], v[230:233], v[16:19]
	v_mfma_f32_16x16x32_bf16 v[8:11], v[180:183], v[238:241], v[8:11]
	v_mfma_f32_16x16x32_bf16 v[0:3], v[188:191], v[238:241], v[0:3]
	v_mfma_f32_16x16x32_bf16 v[56:59], v[184:187], v[218:221], v[56:59]
	v_mfma_f32_16x16x32_bf16 v[48:51], v[210:213], v[218:221], v[48:51]
	v_mfma_f32_16x16x32_bf16 v[40:43], v[184:187], v[226:229], v[40:43]
	v_mfma_f32_16x16x32_bf16 v[32:35], v[210:213], v[226:229], v[32:35]
	v_mfma_f32_16x16x32_bf16 v[24:27], v[184:187], v[234:237], v[24:27]
	v_mfma_f32_16x16x32_bf16 v[16:19], v[210:213], v[234:237], v[16:19]
	v_mfma_f32_16x16x32_bf16 v[8:11], v[184:187], v[242:245], v[8:11]
	v_mfma_f32_16x16x32_bf16 v[0:3], v[210:213], v[242:245], v[0:3]
	s_setprio 0
	s_barrier
; #define PG8_STAGE(bufoff, gbase, voff) do { _Pragma("unroll") for (int _i = 0; _i < 2; ++_i) \
;         __builtin_amdgcn_global_load_lds((const unsigned*)((const char*)(gbase) + (voff)[_i]), (PG8_LAS unsigned*)(lds + (bufoff) + ldsw + _i * 8192), 16, 0, 0); } while (0)
; #define PG8_LDA(dst, b, h) do { _Pragma("unroll") for (int m = 0; m < 4; ++m) _Pragma("unroll") for (int k = 0; k < 2; ++k) dst[m][k] = *(const PG8_LAS bf16x8*)(lds + PG8_SA(b, h) + aoff + m * 2048 + k * 1024); } while (0)
; #define PG8_LDB(dst, b, h) do { _Pragma("unroll") for (int n = 0; n < 2; ++n) _Pragma("unroll") for (int k = 0; k < 2; ++k) dst[n][k] = *(const PG8_LAS bf16x8*)(lds + PG8_SB(b, h) + boff + n * 2048 + k * 1024); } while (0)
; #define PG8_MMA(ai, bj, At, Bt) do { __builtin_amdgcn_s_setprio(1); _Pragma("unroll") for (int m = 0; m < 4; ++m) _Pragma("unroll") for (int n = 0; n < 2; ++n) _Pragma("unroll") for (int k = 0; k < 2; ++k) \
;         acc[ai][bj][m][n] = __builtin_amdgcn_mfma_f32_16x16x32_bf16(Bt[n][k], At[m][k], acc[ai][bj][m][n], 0, 0, 0); __builtin_amdgcn_s_setprio(0); } while (0)
; #define PG8_WAIT_V(n) asm volatile("s_waitcnt vmcnt(" #n ")" ::: "memory")
; #define PG8_WAIT_L(n) asm volatile("s_waitcnt lgkmcnt(" #n ")" ::: "memory")
; #define PG8_BAR __builtin_amdgcn_s_barrier()
; #define PG8_SCHED __builtin_amdgcn_sched_barrier(0)
; template <class Epi, class Sched, bool ALIGN_EPI = false, bool SP2 = false>
; __device__ __forceinline__ void gemm_phase(PG8_LAS unsigned char* lds, const Gemm g, const Sched& S, const Epi& E) {
;     ...
;             PG8_LDB(B0, 1, 0); PG8_LDB(B1, 1, 1); PG8_SCHED; PG8_LDA(At, 1, 0); PG8_STAGE(PG8_SA(0, 1), a2 + hstep, voffA);
;             PG8_WAIT_V(8); PG8_WAIT_L(0); PG8_BAR; PG8_MMA(0, 0, At, B0); PG8_MMA(0, 1, At, B1); PG8_BAR; PG8_SCHED;
;             PG8_LDA(At, 1, 1); PG8_STAGE(PG8_SB(1, 0), b3, voffB); PG8_STAGE(PG8_SB(1, 1), b3 + hstep, voffB); PG8_STAGE(PG8_SA(1, 0), a3, voffA);
;             PG8_WAIT_V(8); PG8_WAIT_L(0); PG8_BAR; PG8_MMA(1, 0, At, B0); PG8_MMA(1, 1, At, B1); PG8_BAR; PG8_SCHED;
	ds_read_b128 v[140:143], v254 offset:32768
	ds_read_b128 v[168:171], v254 offset:33792
	ds_read_b128 v[172:175], v254 offset:34816
	ds_read_b128 v[176:179], v254 offset:35840
	ds_read_b128 v[180:183], v254 offset:49152
	ds_read_b128 v[184:187], v254 offset:50176
	ds_read_b128 v[188:191], v254 offset:51200
	ds_read_b128 v[210:213], v254 offset:52224
	s_add_u32 s18, s18, 0x40000
	s_addc_u32 s19, s19, 0
	s_mov_b32 m0, s33
	ds_read_b128 v[214:217], v165 offset:32768
	ds_read_b128 v[218:221], v165 offset:33792
	ds_read_b128 v[222:225], v165 offset:34816
	ds_read_b128 v[226:229], v165 offset:35840
	ds_read_b128 v[230:233], v165 offset:36864
	ds_read_b128 v[234:237], v165 offset:37888
	ds_read_b128 v[238:241], v165 offset:38912
	ds_read_b128 v[242:245], v165 offset:39936
	global_load_lds_dwordx4 v134, s[18:19]
	s_mov_b32 m0, s34
	s_nop 0
	global_load_lds_dwordx4 v130, s[18:19]
	s_waitcnt vmcnt(9)
	s_waitcnt lgkmcnt(0)
	s_barrier
	s_setprio 1
	v_mfma_f32_16x16x32_bf16 v[124:127], v[140:143], v[214:217], v[124:127]
	v_mfma_f32_16x16x32_bf16 v[116:119], v[172:175], v[214:217], v[116:119]
	v_mfma_f32_16x16x32_bf16 v[108:111], v[140:143], v[222:225], v[108:111]
	v_mfma_f32_16x16x32_bf16 v[100:103], v[172:175], v[222:225], v[100:103]
	v_mfma_f32_16x16x32_bf16 v[92:95], v[140:143], v[230:233], v[92:95]
	v_mfma_f32_16x16x32_bf16 v[84:87], v[172:175], v[230:233], v[84:87]
	v_mfma_f32_16x16x32_bf16 v[76:79], v[140:143], v[238:241], v[76:79]
	v_mfma_f32_16x16x32_bf16 v[68:71], v[172:175], v[238:241], v[68:71]
	v_mfma_f32_16x16x32_bf16 v[124:127], v[168:171], v[218:221], v[124:127]
	v_mfma_f32_16x16x32_bf16 v[116:119], v[176:179], v[218:221], v[116:119]
	v_mfma_f32_16x16x32_bf16 v[108:111], v[168:171], v[226:229], v[108:111]
	v_mfma_f32_16x16x32_bf16 v[100:103], v[176:179], v[226:229], v[100:103]
	v_mfma_f32_16x16x32_bf16 v[92:95], v[168:171], v[234:237], v[92:95]
	v_mfma_f32_16x16x32_bf16 v[84:87], v[176:179], v[234:237], v[84:87]
	v_mfma_f32_16x16x32_bf16 v[76:79], v[168:171], v[242:245], v[76:79]
	v_mfma_f32_16x16x32_bf16 v[68:71], v[176:179], v[242:245], v[68:71]
	v_mfma_f32_16x16x32_bf16 v[120:123], v[180:183], v[214:217], v[120:123]
	v_mfma_f32_16x16x32_bf16 v[112:115], v[188:191], v[214:217], v[112:115]
	v_mfma_f32_16x16x32_bf16 v[104:107], v[180:183], v[222:225], v[104:107]
	v_mfma_f32_16x16x32_bf16 v[96:99], v[188:191], v[222:225], v[96:99]
	v_mfma_f32_16x16x32_bf16 v[88:91], v[180:183], v[230:233], v[88:91]
	v_mfma_f32_16x16x32_bf16 v[80:83], v[188:191], v[230:233], v[80:83]
	v_mfma_f32_16x16x32_bf16 v[72:75], v[180:183], v[238:241], v[72:75]
	v_mfma_f32_16x16x32_bf16 v[64:67], v[188:191], v[238:241], v[64:67]
	v_mfma_f32_16x16x32_bf16 v[120:123], v[184:187], v[218:221], v[120:123]
	v_mfma_f32_16x16x32_bf16 v[112:115], v[210:213], v[218:221], v[112:115]
	v_mfma_f32_16x16x32_bf16 v[104:107], v[184:187], v[226:229], v[104:107]
	v_mfma_f32_16x16x32_bf16 v[96:99], v[210:213], v[226:229], v[96:99]
	v_mfma_f32_16x16x32_bf16 v[88:91], v[184:187], v[234:237], v[88:91]
	v_mfma_f32_16x16x32_bf16 v[80:83], v[210:213], v[234:237], v[80:83]
	v_mfma_f32_16x16x32_bf16 v[72:75], v[184:187], v[242:245], v[72:75]
	v_mfma_f32_16x16x32_bf16 v[64:67], v[210:213], v[242:245], v[64:67]
	s_setprio 0
	s_barrier
	s_mov_b32 m0, s37
	s_add_u32 s16, s16, 0x40080
	s_addc_u32 s17, s17, 0
	ds_read_b128 v[214:217], v165 offset:49152
	ds_read_b128 v[218:221], v165 offset:50176
	ds_read_b128 v[222:225], v165 offset:51200
	ds_read_b128 v[226:229], v165 offset:52224
	ds_read_b128 v[230:233], v165 offset:53248
	ds_read_b128 v[234:237], v165 offset:54272
	ds_read_b128 v[238:241], v165 offset:55296
	ds_read_b128 v[242:245], v165 offset:56320
	s_add_u32 s98, s16, 0xfffc0000
	s_addc_u32 s99, s17, -1
	global_load_lds_dwordx4 v132, s[98:99]
	s_mov_b32 m0, s38
	s_nop 0
	global_load_lds_dwordx4 v128, s[98:99]
	s_mov_b32 m0, s41
	s_nop 0
	global_load_lds_dwordx4 v132, s[16:17]
	s_mov_b32 m0, s42
	s_nop 0
	global_load_lds_dwordx4 v128, s[16:17]
	s_mov_b32 m0, s39
	s_nop 0
	s_add_u32 s100, s18, 0xfffc0080
	s_addc_u32 s101, s19, -1
	global_load_lds_dwordx4 v134, s[100:101]
	s_mov_b32 m0, s40
	s_nop 0
	global_load_lds_dwordx4 v130, s[100:101]
	s_waitcnt vmcnt(9)
	s_waitcnt lgkmcnt(0)
	s_barrier
	s_setprio 1
	v_mfma_f32_16x16x32_bf16 v[60:63], v[140:143], v[214:217], v[60:63]
	v_mfma_f32_16x16x32_bf16 v[52:55], v[172:175], v[214:217], v[52:55]
	v_mfma_f32_16x16x32_bf16 v[44:47], v[140:143], v[222:225], v[44:47]
	v_mfma_f32_16x16x32_bf16 v[36:39], v[172:175], v[222:225], v[36:39]
	v_mfma_f32_16x16x32_bf16 v[28:31], v[140:143], v[230:233], v[28:31]
	v_mfma_f32_16x16x32_bf16 v[20:23], v[172:175], v[230:233], v[20:23]
	v_mfma_f32_16x16x32_bf16 v[12:15], v[140:143], v[238:241], v[12:15]
	v_mfma_f32_16x16x32_bf16 v[4:7], v[172:175], v[238:241], v[4:7]
	v_mfma_f32_16x16x32_bf16 v[60:63], v[168:171], v[218:221], v[60:63]
	v_mfma_f32_16x16x32_bf16 v[52:55], v[176:179], v[218:221], v[52:55]
	v_mfma_f32_16x16x32_bf16 v[44:47], v[168:171], v[226:229], v[44:47]
	v_mfma_f32_16x16x32_bf16 v[36:39], v[176:179], v[226:229], v[36:39]
	v_mfma_f32_16x16x32_bf16 v[28:31], v[168:171], v[234:237], v[28:31]
	v_mfma_f32_16x16x32_bf16 v[20:23], v[176:179], v[234:237], v[20:23]
	v_mfma_f32_16x16x32_bf16 v[12:15], v[168:171], v[242:245], v[12:15]
	v_mfma_f32_16x16x32_bf16 v[4:7], v[176:179], v[242:245], v[4:7]
	v_mfma_f32_16x16x32_bf16 v[56:59], v[180:183], v[214:217], v[56:59]
	v_mfma_f32_16x16x32_bf16 v[48:51], v[188:191], v[214:217], v[48:51]
	v_mfma_f32_16x16x32_bf16 v[40:43], v[180:183], v[222:225], v[40:43]
	v_mfma_f32_16x16x32_bf16 v[32:35], v[188:191], v[222:225], v[32:35]
	v_mfma_f32_16x16x32_bf16 v[24:27], v[180:183], v[230:233], v[24:27]
	v_mfma_f32_16x16x32_bf16 v[16:19], v[188:191], v[230:233], v[16:19]
	v_mfma_f32_16x16x32_bf16 v[8:11], v[180:183], v[238:241], v[8:11]
	v_mfma_f32_16x16x32_bf16 v[0:3], v[188:191], v[238:241], v[0:3]
	v_mfma_f32_16x16x32_bf16 v[56:59], v[184:187], v[218:221], v[56:59]
	v_mfma_f32_16x16x32_bf16 v[48:51], v[210:213], v[218:221], v[48:51]
	v_mfma_f32_16x16x32_bf16 v[40:43], v[184:187], v[226:229], v[40:43]
	v_mfma_f32_16x16x32_bf16 v[32:35], v[210:213], v[226:229], v[32:35]
	v_mfma_f32_16x16x32_bf16 v[24:27], v[184:187], v[234:237], v[24:27]
	v_mfma_f32_16x16x32_bf16 v[16:19], v[210:213], v[234:237], v[16:19]
	v_mfma_f32_16x16x32_bf16 v[8:11], v[184:187], v[242:245], v[8:11]
	v_mfma_f32_16x16x32_bf16 v[0:3], v[210:213], v[242:245], v[0:3]
	s_setprio 0
	s_barrier
	s_add_i32 s53, s53, 2
	s_add_u32 s14, s14, 0x100
	s_addc_u32 s15, s15, 0
	s_add_u32 s51, s51, 0x100
	s_addc_u32 s52, s52, 0
; #define PG8_STAGE(bufoff, gbase, voff) do { _Pragma("unroll") for (int _i = 0; _i < 2; ++_i) \
;         __builtin_amdgcn_global_load_lds((const unsigned*)((const char*)(gbase) + (voff)[_i]), (PG8_LAS unsigned*)(lds + (bufoff) + ldsw + _i * 8192), 16, 0, 0); } while (0)
; #define PG8_LDA(dst, b, h) do { _Pragma("unroll") for (int m = 0; m < 4; ++m) _Pragma("unroll") for (int k = 0; k < 2; ++k) dst[m][k] = *(const PG8_LAS bf16x8*)(lds + PG8_SA(b, h) + aoff + m * 2048 + k * 1024); } while (0)
; #define PG8_LDB(dst, b, h) do { _Pragma("unroll") for (int n = 0; n < 2; ++n) _Pragma("unroll") for (int k = 0; k < 2; ++k) dst[n][k] = *(const PG8_LAS bf16x8*)(lds + PG8_SB(b, h) + boff + n * 2048 + k * 1024); } while (0)
; #define PG8_WAIT_V(n) asm volatile("s_waitcnt vmcnt(" #n ")" ::: "memory")
; #define PG8_WAIT_L(n) asm volatile("s_waitcnt lgkmcnt(" #n ")" ::: "memory")
; #define PG8_BAR __builtin_amdgcn_s_barrier()
;     __device__ __forceinline__ void operator()(const f32x4 (&acc)[2][2][4][2], const Unit& u, int ui, int wr, int wc, int fr, int fq) const {
;     ...
;                 __builtin_nontemporal_store(w, (u32x4*)(H + (size_t)row * ldh + col0)); }
; template <class Epi, class Sched, bool ALIGN_EPI = false, bool SP2 = false>
; __device__ __forceinline__ void gemm_phase(PG8_LAS unsigned char* lds, const Gemm g, const Sched& S, const Epi& E) {
;     ...
;             PG8_LDB(B0, 0, 0); PG8_LDB(B1, 0, 1); PG8_SCHED; PG8_LDA(At, 0, 0); PG8_STAGE(PG8_SA(1, 1), a1 + hstep, voffA);
;             PG8_WAIT_V(8); PG8_WAIT_L(0); PG8_BAR; PG8_MMA(0, 0, At, B0); PG8_MMA(0, 1, At, B1); PG8_BAR; PG8_SCHED;
;             PG8_LDA(At, 0, 1); PG8_STAGE(PG8_SB(0, 0), b2, voffB); PG8_STAGE(PG8_SB(0, 1), b2 + hstep, voffB); PG8_STAGE(PG8_SA(0, 0), a2, voffA);
;             PG8_WAIT_V(8); PG8_WAIT_L(0); PG8_BAR; PG8_MMA(1, 0, At, B0); PG8_MMA(1, 1, At, B1); PG8_BAR; PG8_SCHED;
;             PG8_LDB(B0, 1, 0); PG8_LDB(B1, 1, 1); PG8_SCHED; PG8_LDA(At, 1, 0); PG8_STAGE(PG8_SA(0, 1), a2 + hstep, voffA);
;             PG8_WAIT_V(8); PG8_WAIT_L(0); PG8_BAR; PG8_MMA(0, 0, At, B0); PG8_MMA(0, 1, At, B1); PG8_BAR; PG8_SCHED;
;             PG8_LDA(At, 1, 1); PG8_STAGE(PG8_SB(1, 0), b3, voffB); PG8_STAGE(PG8_SB(1, 1), b3 + hstep, voffB); PG8_STAGE(PG8_SA(1, 0), a3, voffA);
;             PG8_WAIT_V(8); PG8_WAIT_L(0); PG8_BAR; PG8_MMA(1, 0, At, B0); PG8_MMA(1, 1, At, B1); PG8_BAR; PG8_SCHED;
.Lup_sbody_2:
	ds_read_b128 v[140:143], v254
	ds_read_b128 v[168:171], v254 offset:1024
	ds_read_b128 v[172:175], v254 offset:2048
	ds_read_b128 v[176:179], v254 offset:3072
	ds_read_b128 v[180:183], v254 offset:16384
	ds_read_b128 v[184:187], v254 offset:17408
	ds_read_b128 v[188:191], v254 offset:18432
	ds_read_b128 v[210:213], v254 offset:19456
	s_add_u32 s16, s14, 0xfffc0080
	s_addc_u32 s17, s15, -1
	s_cmp_eq_u32 s53, 12
	s_cselect_b32 s19, s7, s17
	s_cselect_b32 s18, s49, s16
	s_cselect_b32 s17, s5, s52
	s_cselect_b32 s16, s50, s51
	s_mov_b32 m0, s43
	ds_read_b128 v[214:217], v165
	ds_read_b128 v[218:221], v165 offset:1024
	ds_read_b128 v[222:225], v165 offset:2048
	ds_read_b128 v[226:229], v165 offset:3072
	ds_read_b128 v[230:233], v165 offset:4096
	ds_read_b128 v[234:237], v165 offset:5120
	ds_read_b128 v[238:241], v165 offset:6144
	ds_read_b128 v[242:245], v165 offset:7168
	global_load_lds_dwordx4 v136, s[14:15]
	s_mov_b32 m0, s44
	s_nop 0
	global_load_lds_dwordx4 v138, s[14:15]
	s_waitcnt vmcnt(8)
	s_waitcnt lgkmcnt(0)
	s_barrier
	s_setprio 1
	v_mfma_f32_16x16x32_bf16 v[124:127], v[140:143], v[214:217], v[124:127]
	v_mfma_f32_16x16x32_bf16 v[116:119], v[172:175], v[214:217], v[116:119]
	v_mfma_f32_16x16x32_bf16 v[108:111], v[140:143], v[222:225], v[108:111]
	v_mfma_f32_16x16x32_bf16 v[100:103], v[172:175], v[222:225], v[100:103]
	v_mfma_f32_16x16x32_bf16 v[92:95], v[140:143], v[230:233], v[92:95]
	v_mfma_f32_16x16x32_bf16 v[84:87], v[172:175], v[230:233], v[84:87]
	v_mfma_f32_16x16x32_bf16 v[76:79], v[140:143], v[238:241], v[76:79]
	v_mfma_f32_16x16x32_bf16 v[68:71], v[172:175], v[238:241], v[68:71]
	v_mfma_f32_16x16x32_bf16 v[124:127], v[168:171], v[218:221], v[124:127]
	v_mfma_f32_16x16x32_bf16 v[116:119], v[176:179], v[218:221], v[116:119]
	v_mfma_f32_16x16x32_bf16 v[108:111], v[168:171], v[226:229], v[108:111]
	v_mfma_f32_16x16x32_bf16 v[100:103], v[176:179], v[226:229], v[100:103]
	v_mfma_f32_16x16x32_bf16 v[92:95], v[168:171], v[234:237], v[92:95]
	v_mfma_f32_16x16x32_bf16 v[84:87], v[176:179], v[234:237], v[84:87]
	v_mfma_f32_16x16x32_bf16 v[76:79], v[168:171], v[242:245], v[76:79]
	v_mfma_f32_16x16x32_bf16 v[68:71], v[176:179], v[242:245], v[68:71]
	v_mfma_f32_16x16x32_bf16 v[120:123], v[180:183], v[214:217], v[120:123]
	v_mfma_f32_16x16x32_bf16 v[112:115], v[188:191], v[214:217], v[112:115]
	v_mfma_f32_16x16x32_bf16 v[104:107], v[180:183], v[222:225], v[104:107]
	v_mfma_f32_16x16x32_bf16 v[96:99], v[188:191], v[222:225], v[96:99]
	v_mfma_f32_16x16x32_bf16 v[88:91], v[180:183], v[230:233], v[88:91]
	v_mfma_f32_16x16x32_bf16 v[80:83], v[188:191], v[230:233], v[80:83]
	v_mfma_f32_16x16x32_bf16 v[72:75], v[180:183], v[238:241], v[72:75]
	v_mfma_f32_16x16x32_bf16 v[64:67], v[188:191], v[238:241], v[64:67]
	v_mfma_f32_16x16x32_bf16 v[120:123], v[184:187], v[218:221], v[120:123]
	v_mfma_f32_16x16x32_bf16 v[112:115], v[210:213], v[218:221], v[112:115]
	v_mfma_f32_16x16x32_bf16 v[104:107], v[184:187], v[226:229], v[104:107]
	v_mfma_f32_16x16x32_bf16 v[96:99], v[210:213], v[226:229], v[96:99]
	v_mfma_f32_16x16x32_bf16 v[88:91], v[184:187], v[234:237], v[88:91]
	v_mfma_f32_16x16x32_bf16 v[80:83], v[210:213], v[234:237], v[80:83]
	v_mfma_f32_16x16x32_bf16 v[72:75], v[184:187], v[242:245], v[72:75]
	v_mfma_f32_16x16x32_bf16 v[64:67], v[210:213], v[242:245], v[64:67]
	s_setprio 0
	s_barrier
	s_mov_b32 m0, s27
	s_add_u32 s54, s16, 0x40000
	s_addc_u32 s55, s17, 0
	ds_read_b128 v[214:217], v165 offset:16384
	ds_read_b128 v[218:221], v165 offset:17408
	ds_read_b128 v[222:225], v165 offset:18432
	ds_read_b128 v[226:229], v165 offset:19456
	ds_read_b128 v[230:233], v165 offset:20480
	ds_read_b128 v[234:237], v165 offset:21504
	ds_read_b128 v[238:241], v165 offset:22528
	ds_read_b128 v[242:245], v165 offset:23552
	global_load_lds_dwordx4 v132, s[16:17]
	s_mov_b32 m0, s28
	s_nop 0
	global_load_lds_dwordx4 v128, s[16:17]
	s_mov_b32 m0, s29
	s_nop 0
	global_load_lds_dwordx4 v132, s[54:55]
	s_mov_b32 m0, s30
	s_nop 0
	global_load_lds_dwordx4 v128, s[54:55]
	s_mov_b32 m0, s22
	s_nop 0
	global_load_lds_dwordx4 v134, s[18:19]
	s_mov_b32 m0, s31
	s_nop 0
	global_load_lds_dwordx4 v130, s[18:19]
	s_add_u32 s100, s20, 0xdc000
	s_addc_u32 s101, s21, 0
	global_store_dwordx4 v255, v[158:161], s[100:101] nt
	s_waitcnt vmcnt(9)
	s_waitcnt lgkmcnt(0)
	s_barrier
	s_setprio 1
	v_mfma_f32_16x16x32_bf16 v[60:63], v[140:143], v[214:217], v[60:63]
	v_mfma_f32_16x16x32_bf16 v[52:55], v[172:175], v[214:217], v[52:55]
	v_mfma_f32_16x16x32_bf16 v[44:47], v[140:143], v[222:225], v[44:47]
	v_mfma_f32_16x16x32_bf16 v[36:39], v[172:175], v[222:225], v[36:39]
	v_mfma_f32_16x16x32_bf16 v[28:31], v[140:143], v[230:233], v[28:31]
	v_mfma_f32_16x16x32_bf16 v[20:23], v[172:175], v[230:233], v[20:23]
	v_mfma_f32_16x16x32_bf16 v[12:15], v[140:143], v[238:241], v[12:15]
	v_mfma_f32_16x16x32_bf16 v[4:7], v[172:175], v[238:241], v[4:7]
	v_mfma_f32_16x16x32_bf16 v[60:63], v[168:171], v[218:221], v[60:63]
	v_mfma_f32_16x16x32_bf16 v[52:55], v[176:179], v[218:221], v[52:55]
	v_mfma_f32_16x16x32_bf16 v[44:47], v[168:171], v[226:229], v[44:47]
	v_mfma_f32_16x16x32_bf16 v[36:39], v[176:179], v[226:229], v[36:39]
	v_mfma_f32_16x16x32_bf16 v[28:31], v[168:171], v[234:237], v[28:31]
	v_mfma_f32_16x16x32_bf16 v[20:23], v[176:179], v[234:237], v[20:23]
	v_mfma_f32_16x16x32_bf16 v[12:15], v[168:171], v[242:245], v[12:15]
	v_mfma_f32_16x16x32_bf16 v[4:7], v[176:179], v[242:245], v[4:7]
	v_mfma_f32_16x16x32_bf16 v[56:59], v[180:183], v[214:217], v[56:59]
	v_mfma_f32_16x16x32_bf16 v[48:51], v[188:191], v[214:217], v[48:51]
	v_mfma_f32_16x16x32_bf16 v[40:43], v[180:183], v[222:225], v[40:43]
	v_mfma_f32_16x16x32_bf16 v[32:35], v[188:191], v[222:225], v[32:35]
	v_mfma_f32_16x16x32_bf16 v[24:27], v[180:183], v[230:233], v[24:27]
	v_mfma_f32_16x16x32_bf16 v[16:19], v[188:191], v[230:233], v[16:19]
	v_mfma_f32_16x16x32_bf16 v[8:11], v[180:183], v[238:241], v[8:11]
	v_mfma_f32_16x16x32_bf16 v[0:3], v[188:191], v[238:241], v[0:3]
	v_mfma_f32_16x16x32_bf16 v[56:59], v[184:187], v[218:221], v[56:59]
	v_mfma_f32_16x16x32_bf16 v[48:51], v[210:213], v[218:221], v[48:51]
	v_mfma_f32_16x16x32_bf16 v[40:43], v[184:187], v[226:229], v[40:43]
	v_mfma_f32_16x16x32_bf16 v[32:35], v[210:213], v[226:229], v[32:35]
	v_mfma_f32_16x16x32_bf16 v[24:27], v[184:187], v[234:237], v[24:27]
	v_mfma_f32_16x16x32_bf16 v[16:19], v[210:213], v[234:237], v[16:19]
	v_mfma_f32_16x16x32_bf16 v[8:11], v[184:187], v[242:245], v[8:11]
	v_mfma_f32_16x16x32_bf16 v[0:3], v[210:213], v[242:245], v[0:3]
	s_setprio 0
	s_barrier
; #define PG8_STAGE(bufoff, gbase, voff) do { _Pragma("unroll") for (int _i = 0; _i < 2; ++_i) \
;         __builtin_amdgcn_global_load_lds((const unsigned*)((const char*)(gbase) + (voff)[_i]), (PG8_LAS unsigned*)(lds + (bufoff) + ldsw + _i * 8192), 16, 0, 0); } while (0)
; #define PG8_LDA(dst, b, h) do { _Pragma("unroll") for (int m = 0; m < 4; ++m) _Pragma("unroll") for (int k = 0; k < 2; ++k) dst[m][k] = *(const PG8_LAS bf16x8*)(lds + PG8_SA(b, h) + aoff + m * 2048 + k * 1024); } while (0)
; #define PG8_LDB(dst, b, h) do { _Pragma("unroll") for (int n = 0; n < 2; ++n) _Pragma("unroll") for (int k = 0; k < 2; ++k) dst[n][k] = *(const PG8_LAS bf16x8*)(lds + PG8_SB(b, h) + boff + n * 2048 + k * 1024); } while (0)
; #define PG8_MMA(ai, bj, At, Bt) do { __builtin_amdgcn_s_setprio(1); _Pragma("unroll") for (int m = 0; m < 4; ++m) _Pragma("unroll") for (int n = 0; n < 2; ++n) _Pragma("unroll") for (int k = 0; k < 2; ++k) \
;         acc[ai][bj][m][n] = __builtin_amdgcn_mfma_f32_16x16x32_bf16(Bt[n][k], At[m][k], acc[ai][bj][m][n], 0, 0, 0); __builtin_amdgcn_s_setprio(0); } while (0)
; #define PG8_WAIT_V(n) asm volatile("s_waitcnt vmcnt(" #n ")" ::: "memory")
; #define PG8_WAIT_L(n) asm volatile("s_waitcnt lgkmcnt(" #n ")" ::: "memory")
; #define PG8_BAR __builtin_amdgcn_s_barrier()
; #define PG8_SCHED __builtin_amdgcn_sched_barrier(0)
; template <class Epi, class Sched, bool ALIGN_EPI = false, bool SP2 = false>
; __device__ __forceinline__ void gemm_phase(PG8_LAS unsigned char* lds, const Gemm g, const Sched& S, const Epi& E) {
;     ...
;             PG8_LDB(B0, 1, 0); PG8_LDB(B1, 1, 1); PG8_SCHED; PG8_LDA(At, 1, 0); PG8_STAGE(PG8_SA(0, 1), a2 + hstep, voffA);
;             PG8_WAIT_V(8); PG8_WAIT_L(0); PG8_BAR; PG8_MMA(0, 0, At, B0); PG8_MMA(0, 1, At, B1); PG8_BAR; PG8_SCHED;
;             PG8_LDA(At, 1, 1); PG8_STAGE(PG8_SB(1, 0), b3, voffB); PG8_STAGE(PG8_SB(1, 1), b3 + hstep, voffB); PG8_STAGE(PG8_SA(1, 0), a3, voffA);
;             PG8_WAIT_V(8); PG8_WAIT_L(0); PG8_BAR; PG8_MMA(1, 0, At, B0); PG8_MMA(1, 1, At, B1); PG8_BAR; PG8_SCHED;
	ds_read_b128 v[140:143], v254 offset:32768
	ds_read_b128 v[168:171], v254 offset:33792
	ds_read_b128 v[172:175], v254 offset:34816
	ds_read_b128 v[176:179], v254 offset:35840
	ds_read_b128 v[180:183], v254 offset:49152
	ds_read_b128 v[184:187], v254 offset:50176
	ds_read_b128 v[188:191], v254 offset:51200
	ds_read_b128 v[210:213], v254 offset:52224
	s_add_u32 s18, s18, 0x40000
	s_addc_u32 s19, s19, 0
	s_mov_b32 m0, s33
	ds_read_b128 v[214:217], v165 offset:32768
	ds_read_b128 v[218:221], v165 offset:33792
	ds_read_b128 v[222:225], v165 offset:34816
	ds_read_b128 v[226:229], v165 offset:35840
	ds_read_b128 v[230:233], v165 offset:36864
	ds_read_b128 v[234:237], v165 offset:37888
	ds_read_b128 v[238:241], v165 offset:38912
	ds_read_b128 v[242:245], v165 offset:39936
	global_load_lds_dwordx4 v134, s[18:19]
	s_mov_b32 m0, s34
	s_nop 0
	global_load_lds_dwordx4 v130, s[18:19]
	s_waitcnt vmcnt(9)
	s_waitcnt lgkmcnt(0)
	s_barrier
	s_setprio 1
	v_mfma_f32_16x16x32_bf16 v[124:127], v[140:143], v[214:217], v[124:127]
	v_mfma_f32_16x16x32_bf16 v[116:119], v[172:175], v[214:217], v[116:119]
	v_mfma_f32_16x16x32_bf16 v[108:111], v[140:143], v[222:225], v[108:111]
	v_mfma_f32_16x16x32_bf16 v[100:103], v[172:175], v[222:225], v[100:103]
	v_mfma_f32_16x16x32_bf16 v[92:95], v[140:143], v[230:233], v[92:95]
	v_mfma_f32_16x16x32_bf16 v[84:87], v[172:175], v[230:233], v[84:87]
	v_mfma_f32_16x16x32_bf16 v[76:79], v[140:143], v[238:241], v[76:79]
	v_mfma_f32_16x16x32_bf16 v[68:71], v[172:175], v[238:241], v[68:71]
	v_mfma_f32_16x16x32_bf16 v[124:127], v[168:171], v[218:221], v[124:127]
	v_mfma_f32_16x16x32_bf16 v[116:119], v[176:179], v[218:221], v[116:119]
	v_mfma_f32_16x16x32_bf16 v[108:111], v[168:171], v[226:229], v[108:111]
	v_mfma_f32_16x16x32_bf16 v[100:103], v[176:179], v[226:229], v[100:103]
	v_mfma_f32_16x16x32_bf16 v[92:95], v[168:171], v[234:237], v[92:95]
	v_mfma_f32_16x16x32_bf16 v[84:87], v[176:179], v[234:237], v[84:87]
	v_mfma_f32_16x16x32_bf16 v[76:79], v[168:171], v[242:245], v[76:79]
	v_mfma_f32_16x16x32_bf16 v[68:71], v[176:179], v[242:245], v[68:71]
	v_mfma_f32_16x16x32_bf16 v[120:123], v[180:183], v[214:217], v[120:123]
	v_mfma_f32_16x16x32_bf16 v[112:115], v[188:191], v[214:217], v[112:115]
	v_mfma_f32_16x16x32_bf16 v[104:107], v[180:183], v[222:225], v[104:107]
	v_mfma_f32_16x16x32_bf16 v[96:99], v[188:191], v[222:225], v[96:99]
	v_mfma_f32_16x16x32_bf16 v[88:91], v[180:183], v[230:233], v[88:91]
	v_mfma_f32_16x16x32_bf16 v[80:83], v[188:191], v[230:233], v[80:83]
	v_mfma_f32_16x16x32_bf16 v[72:75], v[180:183], v[238:241], v[72:75]
	v_mfma_f32_16x16x32_bf16 v[64:67], v[188:191], v[238:241], v[64:67]
	v_mfma_f32_16x16x32_bf16 v[120:123], v[184:187], v[218:221], v[120:123]
	v_mfma_f32_16x16x32_bf16 v[112:115], v[210:213], v[218:221], v[112:115]
	v_mfma_f32_16x16x32_bf16 v[104:107], v[184:187], v[226:229], v[104:107]
	v_mfma_f32_16x16x32_bf16 v[96:99], v[210:213], v[226:229], v[96:99]
	v_mfma_f32_16x16x32_bf16 v[88:91], v[184:187], v[234:237], v[88:91]
	v_mfma_f32_16x16x32_bf16 v[80:83], v[210:213], v[234:237], v[80:83]
	v_mfma_f32_16x16x32_bf16 v[72:75], v[184:187], v[242:245], v[72:75]
	v_mfma_f32_16x16x32_bf16 v[64:67], v[210:213], v[242:245], v[64:67]
	s_setprio 0
	s_barrier
	s_mov_b32 m0, s37
	s_add_u32 s16, s16, 0x40080
	s_addc_u32 s17, s17, 0
	ds_read_b128 v[214:217], v165 offset:49152
	ds_read_b128 v[218:221], v165 offset:50176
	ds_read_b128 v[222:225], v165 offset:51200
	ds_read_b128 v[226:229], v165 offset:52224
	ds_read_b128 v[230:233], v165 offset:53248
	ds_read_b128 v[234:237], v165 offset:54272
	ds_read_b128 v[238:241], v165 offset:55296
	ds_read_b128 v[242:245], v165 offset:56320
	s_add_u32 s98, s16, 0xfffc0000
	s_addc_u32 s99, s17, -1
	global_load_lds_dwordx4 v132, s[98:99]
	s_mov_b32 m0, s38
	s_nop 0
	global_load_lds_dwordx4 v128, s[98:99]
	s_mov_b32 m0, s41
	s_nop 0
	global_load_lds_dwordx4 v132, s[16:17]
	s_mov_b32 m0, s42
	s_nop 0
	global_load_lds_dwordx4 v128, s[16:17]
	s_mov_b32 m0, s39
	s_nop 0
	s_add_u32 s100, s18, 0xfffc0080
	s_addc_u32 s101, s19, -1
	global_load_lds_dwordx4 v134, s[100:101]
	s_mov_b32 m0, s40
	s_nop 0
	global_load_lds_dwordx4 v130, s[100:101]
	s_waitcnt vmcnt(9)
	s_waitcnt lgkmcnt(0)
	s_barrier
	s_setprio 1
	v_mfma_f32_16x16x32_bf16 v[60:63], v[140:143], v[214:217], v[60:63]
	v_mfma_f32_16x16x32_bf16 v[52:55], v[172:175], v[214:217], v[52:55]
	v_mfma_f32_16x16x32_bf16 v[44:47], v[140:143], v[222:225], v[44:47]
	v_mfma_f32_16x16x32_bf16 v[36:39], v[172:175], v[222:225], v[36:39]
	v_mfma_f32_16x16x32_bf16 v[28:31], v[140:143], v[230:233], v[28:31]
	v_mfma_f32_16x16x32_bf16 v[20:23], v[172:175], v[230:233], v[20:23]
	v_mfma_f32_16x16x32_bf16 v[12:15], v[140:143], v[238:241], v[12:15]
	v_mfma_f32_16x16x32_bf16 v[4:7], v[172:175], v[238:241], v[4:7]
	v_mfma_f32_16x16x32_bf16 v[60:63], v[168:171], v[218:221], v[60:63]
	v_mfma_f32_16x16x32_bf16 v[52:55], v[176:179], v[218:221], v[52:55]
	v_mfma_f32_16x16x32_bf16 v[44:47], v[168:171], v[226:229], v[44:47]
	v_mfma_f32_16x16x32_bf16 v[36:39], v[176:179], v[226:229], v[36:39]
	v_mfma_f32_16x16x32_bf16 v[28:31], v[168:171], v[234:237], v[28:31]
	v_mfma_f32_16x16x32_bf16 v[20:23], v[176:179], v[234:237], v[20:23]
	v_mfma_f32_16x16x32_bf16 v[12:15], v[168:171], v[242:245], v[12:15]
	v_mfma_f32_16x16x32_bf16 v[4:7], v[176:179], v[242:245], v[4:7]
	v_mfma_f32_16x16x32_bf16 v[56:59], v[180:183], v[214:217], v[56:59]
	v_mfma_f32_16x16x32_bf16 v[48:51], v[188:191], v[214:217], v[48:51]
	v_mfma_f32_16x16x32_bf16 v[40:43], v[180:183], v[222:225], v[40:43]
	v_mfma_f32_16x16x32_bf16 v[32:35], v[188:191], v[222:225], v[32:35]
	v_mfma_f32_16x16x32_bf16 v[24:27], v[180:183], v[230:233], v[24:27]
	v_mfma_f32_16x16x32_bf16 v[16:19], v[188:191], v[230:233], v[16:19]
	v_mfma_f32_16x16x32_bf16 v[8:11], v[180:183], v[238:241], v[8:11]
	v_mfma_f32_16x16x32_bf16 v[0:3], v[188:191], v[238:241], v[0:3]
	v_mfma_f32_16x16x32_bf16 v[56:59], v[184:187], v[218:221], v[56:59]
	v_mfma_f32_16x16x32_bf16 v[48:51], v[210:213], v[218:221], v[48:51]
	v_mfma_f32_16x16x32_bf16 v[40:43], v[184:187], v[226:229], v[40:43]
	v_mfma_f32_16x16x32_bf16 v[32:35], v[210:213], v[226:229], v[32:35]
	v_mfma_f32_16x16x32_bf16 v[24:27], v[184:187], v[234:237], v[24:27]
	v_mfma_f32_16x16x32_bf16 v[16:19], v[210:213], v[234:237], v[16:19]
	v_mfma_f32_16x16x32_bf16 v[8:11], v[184:187], v[242:245], v[8:11]
	v_mfma_f32_16x16x32_bf16 v[0:3], v[210:213], v[242:245], v[0:3]
	s_setprio 0
	s_barrier
	s_add_i32 s53, s53, 2
	s_add_u32 s14, s14, 0x100
	s_addc_u32 s15, s15, 0
	s_add_u32 s51, s51, 0x100
	s_addc_u32 s52, s52, 0
; #define PG8_STAGE(bufoff, gbase, voff) do { _Pragma("unroll") for (int _i = 0; _i < 2; ++_i) \
;         __builtin_amdgcn_global_load_lds((const unsigned*)((const char*)(gbase) + (voff)[_i]), (PG8_LAS unsigned*)(lds + (bufoff) + ldsw + _i * 8192), 16, 0, 0); } while (0)
; #define PG8_LDA(dst, b, h) do { _Pragma("unroll") for (int m = 0; m < 4; ++m) _Pragma("unroll") for (int k = 0; k < 2; ++k) dst[m][k] = *(const PG8_LAS bf16x8*)(lds + PG8_SA(b, h) + aoff + m * 2048 + k * 1024); } while (0)
; #define PG8_LDB(dst, b, h) do { _Pragma("unroll") for (int n = 0; n < 2; ++n) _Pragma("unroll") for (int k = 0; k < 2; ++k) dst[n][k] = *(const PG8_LAS bf16x8*)(lds + PG8_SB(b, h) + boff + n * 2048 + k * 1024); } while (0)
; #define PG8_WAIT_V(n) asm volatile("s_waitcnt vmcnt(" #n ")" ::: "memory")
; #define PG8_WAIT_L(n) asm volatile("s_waitcnt lgkmcnt(" #n ")" ::: "memory")
; #define PG8_BAR __builtin_amdgcn_s_barrier()
;     __device__ __forceinline__ void operator()(const f32x4 (&acc)[2][2][4][2], const Unit& u, int ui, int wr, int wc, int fr, int fq) const {
;     ...
;                 __builtin_nontemporal_store(w, (u32x4*)(H + (size_t)row * ldh + col0)); }
; template <class Epi, class Sched, bool ALIGN_EPI = false, bool SP2 = false>
; __device__ __forceinline__ void gemm_phase(PG8_LAS unsigned char* lds, const Gemm g, const Sched& S, const Epi& E) {
;     ...
;             PG8_LDB(B0, 0, 0); PG8_LDB(B1, 0, 1); PG8_SCHED; PG8_LDA(At, 0, 0); PG8_STAGE(PG8_SA(1, 1), a1 + hstep, voffA);
;             PG8_WAIT_V(8); PG8_WAIT_L(0); PG8_BAR; PG8_MMA(0, 0, At, B0); PG8_MMA(0, 1, At, B1); PG8_BAR; PG8_SCHED;
;             PG8_LDA(At, 0, 1); PG8_STAGE(PG8_SB(0, 0), b2, voffB); PG8_STAGE(PG8_SB(0, 1), b2 + hstep, voffB); PG8_STAGE(PG8_SA(0, 0), a2, voffA);
;             PG8_WAIT_V(8); PG8_WAIT_L(0); PG8_BAR; PG8_MMA(1, 0, At, B0); PG8_MMA(1, 1, At, B1); PG8_BAR; PG8_SCHED;
;             PG8_LDB(B0, 1, 0); PG8_LDB(B1, 1, 1); PG8_SCHED; PG8_LDA(At, 1, 0); PG8_STAGE(PG8_SA(0, 1), a2 + hstep, voffA);
;             PG8_WAIT_V(8); PG8_WAIT_L(0); PG8_BAR; PG8_MMA(0, 0, At, B0); PG8_MMA(0, 1, At, B1); PG8_BAR; PG8_SCHED;
;             PG8_LDA(At, 1, 1); PG8_STAGE(PG8_SB(1, 0), b3, voffB); PG8_STAGE(PG8_SB(1, 1), b3 + hstep, voffB); PG8_STAGE(PG8_SA(1, 0), a3, voffA);
;             PG8_WAIT_V(8); PG8_WAIT_L(0); PG8_BAR; PG8_MMA(1, 0, At, B0); PG8_MMA(1, 1, At, B1); PG8_BAR; PG8_SCHED;
.Lup_sbody_3:
	ds_read_b128 v[140:143], v254
	ds_read_b128 v[168:171], v254 offset:1024
	ds_read_b128 v[172:175], v254 offset:2048
	ds_read_b128 v[176:179], v254 offset:3072
	ds_read_b128 v[180:183], v254 offset:16384
	ds_read_b128 v[184:187], v254 offset:17408
	ds_read_b128 v[188:191], v254 offset:18432
	ds_read_b128 v[210:213], v254 offset:19456
	s_add_u32 s16, s14, 0xfffc0080
	s_addc_u32 s17, s15, -1
	s_cmp_eq_u32 s53, 12
	s_cselect_b32 s19, s7, s17
	s_cselect_b32 s18, s49, s16
	s_cselect_b32 s17, s5, s52
	s_cselect_b32 s16, s50, s51
	s_mov_b32 m0, s43
	ds_read_b128 v[214:217], v165
	ds_read_b128 v[218:221], v165 offset:1024
	ds_read_b128 v[222:225], v165 offset:2048
	ds_read_b128 v[226:229], v165 offset:3072
	ds_read_b128 v[230:233], v165 offset:4096
	ds_read_b128 v[234:237], v165 offset:5120
	ds_read_b128 v[238:241], v165 offset:6144
	ds_read_b128 v[242:245], v165 offset:7168
	global_load_lds_dwordx4 v136, s[14:15]
	s_mov_b32 m0, s44
	s_nop 0
	global_load_lds_dwordx4 v138, s[14:15]
	s_waitcnt vmcnt(8)
	s_waitcnt lgkmcnt(0)
	s_barrier
	s_setprio 1
	v_mfma_f32_16x16x32_bf16 v[124:127], v[140:143], v[214:217], v[124:127]
	v_mfma_f32_16x16x32_bf16 v[116:119], v[172:175], v[214:217], v[116:119]
	v_mfma_f32_16x16x32_bf16 v[108:111], v[140:143], v[222:225], v[108:111]
	v_mfma_f32_16x16x32_bf16 v[100:103], v[172:175], v[222:225], v[100:103]
	v_mfma_f32_16x16x32_bf16 v[92:95], v[140:143], v[230:233], v[92:95]
	v_mfma_f32_16x16x32_bf16 v[84:87], v[172:175], v[230:233], v[84:87]
	v_mfma_f32_16x16x32_bf16 v[76:79], v[140:143], v[238:241], v[76:79]
	v_mfma_f32_16x16x32_bf16 v[68:71], v[172:175], v[238:241], v[68:71]
	v_mfma_f32_16x16x32_bf16 v[124:127], v[168:171], v[218:221], v[124:127]
	v_mfma_f32_16x16x32_bf16 v[116:119], v[176:179], v[218:221], v[116:119]
	v_mfma_f32_16x16x32_bf16 v[108:111], v[168:171], v[226:229], v[108:111]
	v_mfma_f32_16x16x32_bf16 v[100:103], v[176:179], v[226:229], v[100:103]
	v_mfma_f32_16x16x32_bf16 v[92:95], v[168:171], v[234:237], v[92:95]
	v_mfma_f32_16x16x32_bf16 v[84:87], v[176:179], v[234:237], v[84:87]
	v_mfma_f32_16x16x32_bf16 v[76:79], v[168:171], v[242:245], v[76:79]
	v_mfma_f32_16x16x32_bf16 v[68:71], v[176:179], v[242:245], v[68:71]
	v_mfma_f32_16x16x32_bf16 v[120:123], v[180:183], v[214:217], v[120:123]
	v_mfma_f32_16x16x32_bf16 v[112:115], v[188:191], v[214:217], v[112:115]
	v_mfma_f32_16x16x32_bf16 v[104:107], v[180:183], v[222:225], v[104:107]
	v_mfma_f32_16x16x32_bf16 v[96:99], v[188:191], v[222:225], v[96:99]
	v_mfma_f32_16x16x32_bf16 v[88:91], v[180:183], v[230:233], v[88:91]
	v_mfma_f32_16x16x32_bf16 v[80:83], v[188:191], v[230:233], v[80:83]
	v_mfma_f32_16x16x32_bf16 v[72:75], v[180:183], v[238:241], v[72:75]
	v_mfma_f32_16x16x32_bf16 v[64:67], v[188:191], v[238:241], v[64:67]
	v_mfma_f32_16x16x32_bf16 v[120:123], v[184:187], v[218:221], v[120:123]
	v_mfma_f32_16x16x32_bf16 v[112:115], v[210:213], v[218:221], v[112:115]
	v_mfma_f32_16x16x32_bf16 v[104:107], v[184:187], v[226:229], v[104:107]
	v_mfma_f32_16x16x32_bf16 v[96:99], v[210:213], v[226:229], v[96:99]
	v_mfma_f32_16x16x32_bf16 v[88:91], v[184:187], v[234:237], v[88:91]
	v_mfma_f32_16x16x32_bf16 v[80:83], v[210:213], v[234:237], v[80:83]
	v_mfma_f32_16x16x32_bf16 v[72:75], v[184:187], v[242:245], v[72:75]
	v_mfma_f32_16x16x32_bf16 v[64:67], v[210:213], v[242:245], v[64:67]
	s_setprio 0
	s_barrier
	s_mov_b32 m0, s27
	s_add_u32 s54, s16, 0x40000
	s_addc_u32 s55, s17, 0
	ds_read_b128 v[214:217], v165 offset:16384
	ds_read_b128 v[218:221], v165 offset:17408
	ds_read_b128 v[222:225], v165 offset:18432
	ds_read_b128 v[226:229], v165 offset:19456
	ds_read_b128 v[230:233], v165 offset:20480
	ds_read_b128 v[234:237], v165 offset:21504
	ds_read_b128 v[238:241], v165 offset:22528
	ds_read_b128 v[242:245], v165 offset:23552
	global_load_lds_dwordx4 v132, s[16:17]
	s_mov_b32 m0, s28
	s_nop 0
	global_load_lds_dwordx4 v128, s[16:17]
	s_mov_b32 m0, s29
	s_nop 0
	global_load_lds_dwordx4 v132, s[54:55]
	s_mov_b32 m0, s30
	s_nop 0
	global_load_lds_dwordx4 v128, s[54:55]
	s_mov_b32 m0, s22
	s_nop 0
	global_load_lds_dwordx4 v134, s[18:19]
	s_mov_b32 m0, s31
	s_nop 0
	global_load_lds_dwordx4 v130, s[18:19]
	s_add_u32 s100, s20, 0xf2000
	s_addc_u32 s101, s21, 0
	global_store_dwordx4 v255, v[246:249], s[100:101] nt
	s_waitcnt vmcnt(9)
	s_waitcnt lgkmcnt(0)
	s_barrier
	s_setprio 1
	v_mfma_f32_16x16x32_bf16 v[60:63], v[140:143], v[214:217], v[60:63]
	v_mfma_f32_16x16x32_bf16 v[52:55], v[172:175], v[214:217], v[52:55]
	v_mfma_f32_16x16x32_bf16 v[44:47], v[140:143], v[222:225], v[44:47]
	v_mfma_f32_16x16x32_bf16 v[36:39], v[172:175], v[222:225], v[36:39]
	v_mfma_f32_16x16x32_bf16 v[28:31], v[140:143], v[230:233], v[28:31]
	v_mfma_f32_16x16x32_bf16 v[20:23], v[172:175], v[230:233], v[20:23]
	v_mfma_f32_16x16x32_bf16 v[12:15], v[140:143], v[238:241], v[12:15]
	v_mfma_f32_16x16x32_bf16 v[4:7], v[172:175], v[238:241], v[4:7]
	v_mfma_f32_16x16x32_bf16 v[60:63], v[168:171], v[218:221], v[60:63]
	v_mfma_f32_16x16x32_bf16 v[52:55], v[176:179], v[218:221], v[52:55]
	v_mfma_f32_16x16x32_bf16 v[44:47], v[168:171], v[226:229], v[44:47]
	v_mfma_f32_16x16x32_bf16 v[36:39], v[176:179], v[226:229], v[36:39]
	v_mfma_f32_16x16x32_bf16 v[28:31], v[168:171], v[234:237], v[28:31]
	v_mfma_f32_16x16x32_bf16 v[20:23], v[176:179], v[234:237], v[20:23]
	v_mfma_f32_16x16x32_bf16 v[12:15], v[168:171], v[242:245], v[12:15]
	v_mfma_f32_16x16x32_bf16 v[4:7], v[176:179], v[242:245], v[4:7]
	v_mfma_f32_16x16x32_bf16 v[56:59], v[180:183], v[214:217], v[56:59]
	v_mfma_f32_16x16x32_bf16 v[48:51], v[188:191], v[214:217], v[48:51]
	v_mfma_f32_16x16x32_bf16 v[40:43], v[180:183], v[222:225], v[40:43]
	v_mfma_f32_16x16x32_bf16 v[32:35], v[188:191], v[222:225], v[32:35]
	v_mfma_f32_16x16x32_bf16 v[24:27], v[180:183], v[230:233], v[24:27]
	v_mfma_f32_16x16x32_bf16 v[16:19], v[188:191], v[230:233], v[16:19]
	v_mfma_f32_16x16x32_bf16 v[8:11], v[180:183], v[238:241], v[8:11]
	v_mfma_f32_16x16x32_bf16 v[0:3], v[188:191], v[238:241], v[0:3]
	v_mfma_f32_16x16x32_bf16 v[56:59], v[184:187], v[218:221], v[56:59]
	v_mfma_f32_16x16x32_bf16 v[48:51], v[210:213], v[218:221], v[48:51]
	v_mfma_f32_16x16x32_bf16 v[40:43], v[184:187], v[226:229], v[40:43]
	v_mfma_f32_16x16x32_bf16 v[32:35], v[210:213], v[226:229], v[32:35]
	v_mfma_f32_16x16x32_bf16 v[24:27], v[184:187], v[234:237], v[24:27]
	v_mfma_f32_16x16x32_bf16 v[16:19], v[210:213], v[234:237], v[16:19]
	v_mfma_f32_16x16x32_bf16 v[8:11], v[184:187], v[242:245], v[8:11]
	v_mfma_f32_16x16x32_bf16 v[0:3], v[210:213], v[242:245], v[0:3]
	s_setprio 0
	s_barrier
; #define PG8_STAGE(bufoff, gbase, voff) do { _Pragma("unroll") for (int _i = 0; _i < 2; ++_i) \
;         __builtin_amdgcn_global_load_lds((const unsigned*)((const char*)(gbase) + (voff)[_i]), (PG8_LAS unsigned*)(lds + (bufoff) + ldsw + _i * 8192), 16, 0, 0); } while (0)
; #define PG8_LDA(dst, b, h) do { _Pragma("unroll") for (int m = 0; m < 4; ++m) _Pragma("unroll") for (int k = 0; k < 2; ++k) dst[m][k] = *(const PG8_LAS bf16x8*)(lds + PG8_SA(b, h) + aoff + m * 2048 + k * 1024); } while (0)
; #define PG8_LDB(dst, b, h) do { _Pragma("unroll") for (int n = 0; n < 2; ++n) _Pragma("unroll") for (int k = 0; k < 2; ++k) dst[n][k] = *(const PG8_LAS bf16x8*)(lds + PG8_SB(b, h) + boff + n * 2048 + k * 1024); } while (0)
; #define PG8_MMA(ai, bj, At, Bt) do { __builtin_amdgcn_s_setprio(1); _Pragma("unroll") for (int m = 0; m < 4; ++m) _Pragma("unroll") for (int n = 0; n < 2; ++n) _Pragma("unroll") for (int k = 0; k < 2; ++k) \
;         acc[ai][bj][m][n] = __builtin_amdgcn_mfma_f32_16x16x32_bf16(Bt[n][k], At[m][k], acc[ai][bj][m][n], 0, 0, 0); __builtin_amdgcn_s_setprio(0); } while (0)
; #define PG8_WAIT_V(n) asm volatile("s_waitcnt vmcnt(" #n ")" ::: "memory")
; #define PG8_WAIT_L(n) asm volatile("s_waitcnt lgkmcnt(" #n ")" ::: "memory")
; #define PG8_BAR __builtin_amdgcn_s_barrier()
; #define PG8_SCHED __builtin_amdgcn_sched_barrier(0)
; template <class Epi, class Sched, bool ALIGN_EPI = false, bool SP2 = false>
; __device__ __forceinline__ void gemm_phase(PG8_LAS unsigned char* lds, const Gemm g, const Sched& S, const Epi& E) {
;     ...
;         for (int t = 0; t < nt; t += 2) {
;     ...
;             PG8_LDB(B0, 1, 0); PG8_LDB(B1, 1, 1); PG8_SCHED; PG8_LDA(At, 1, 0); PG8_STAGE(PG8_SA(0, 1), a2 + hstep, voffA);
;             PG8_WAIT_V(8); PG8_WAIT_L(0); PG8_BAR; PG8_MMA(0, 0, At, B0); PG8_MMA(0, 1, At, B1); PG8_BAR; PG8_SCHED;
;             PG8_LDA(At, 1, 1); PG8_STAGE(PG8_SB(1, 0), b3, voffB); PG8_STAGE(PG8_SB(1, 1), b3 + hstep, voffB); PG8_STAGE(PG8_SA(1, 0), a3, voffA);
;             PG8_WAIT_V(8); PG8_WAIT_L(0); PG8_BAR; PG8_MMA(1, 0, At, B0); PG8_MMA(1, 1, At, B1); PG8_BAR; PG8_SCHED;
	ds_read_b128 v[140:143], v254 offset:32768
	ds_read_b128 v[168:171], v254 offset:33792
	ds_read_b128 v[172:175], v254 offset:34816
	ds_read_b128 v[176:179], v254 offset:35840
	ds_read_b128 v[180:183], v254 offset:49152
	ds_read_b128 v[184:187], v254 offset:50176
	ds_read_b128 v[188:191], v254 offset:51200
	ds_read_b128 v[210:213], v254 offset:52224
	s_add_u32 s18, s18, 0x40000
	s_addc_u32 s19, s19, 0
	s_mov_b32 m0, s33
	ds_read_b128 v[214:217], v165 offset:32768
	ds_read_b128 v[218:221], v165 offset:33792
	ds_read_b128 v[222:225], v165 offset:34816
	ds_read_b128 v[226:229], v165 offset:35840
	ds_read_b128 v[230:233], v165 offset:36864
	ds_read_b128 v[234:237], v165 offset:37888
	ds_read_b128 v[238:241], v165 offset:38912
	ds_read_b128 v[242:245], v165 offset:39936
	global_load_lds_dwordx4 v134, s[18:19]
	s_mov_b32 m0, s34
	s_nop 0
	global_load_lds_dwordx4 v130, s[18:19]
	s_waitcnt vmcnt(9)
	s_waitcnt lgkmcnt(0)
	s_barrier
	s_setprio 1
	v_mfma_f32_16x16x32_bf16 v[124:127], v[140:143], v[214:217], v[124:127]
	v_mfma_f32_16x16x32_bf16 v[116:119], v[172:175], v[214:217], v[116:119]
	v_mfma_f32_16x16x32_bf16 v[108:111], v[140:143], v[222:225], v[108:111]
	v_mfma_f32_16x16x32_bf16 v[100:103], v[172:175], v[222:225], v[100:103]
	v_mfma_f32_16x16x32_bf16 v[92:95], v[140:143], v[230:233], v[92:95]
	v_mfma_f32_16x16x32_bf16 v[84:87], v[172:175], v[230:233], v[84:87]
	v_mfma_f32_16x16x32_bf16 v[76:79], v[140:143], v[238:241], v[76:79]
	v_mfma_f32_16x16x32_bf16 v[68:71], v[172:175], v[238:241], v[68:71]
	v_mfma_f32_16x16x32_bf16 v[124:127], v[168:171], v[218:221], v[124:127]
	v_mfma_f32_16x16x32_bf16 v[116:119], v[176:179], v[218:221], v[116:119]
	v_mfma_f32_16x16x32_bf16 v[108:111], v[168:171], v[226:229], v[108:111]
	v_mfma_f32_16x16x32_bf16 v[100:103], v[176:179], v[226:229], v[100:103]
	v_mfma_f32_16x16x32_bf16 v[92:95], v[168:171], v[234:237], v[92:95]
	v_mfma_f32_16x16x32_bf16 v[84:87], v[176:179], v[234:237], v[84:87]
	v_mfma_f32_16x16x32_bf16 v[76:79], v[168:171], v[242:245], v[76:79]
	v_mfma_f32_16x16x32_bf16 v[68:71], v[176:179], v[242:245], v[68:71]
	v_mfma_f32_16x16x32_bf16 v[120:123], v[180:183], v[214:217], v[120:123]
	v_mfma_f32_16x16x32_bf16 v[112:115], v[188:191], v[214:217], v[112:115]
	v_mfma_f32_16x16x32_bf16 v[104:107], v[180:183], v[222:225], v[104:107]
	v_mfma_f32_16x16x32_bf16 v[96:99], v[188:191], v[222:225], v[96:99]
	v_mfma_f32_16x16x32_bf16 v[88:91], v[180:183], v[230:233], v[88:91]
	v_mfma_f32_16x16x32_bf16 v[80:83], v[188:191], v[230:233], v[80:83]
	v_mfma_f32_16x16x32_bf16 v[72:75], v[180:183], v[238:241], v[72:75]
	v_mfma_f32_16x16x32_bf16 v[64:67], v[188:191], v[238:241], v[64:67]
	v_mfma_f32_16x16x32_bf16 v[120:123], v[184:187], v[218:221], v[120:123]
	v_mfma_f32_16x16x32_bf16 v[112:115], v[210:213], v[218:221], v[112:115]
	v_mfma_f32_16x16x32_bf16 v[104:107], v[184:187], v[226:229], v[104:107]
	v_mfma_f32_16x16x32_bf16 v[96:99], v[210:213], v[226:229], v[96:99]
	v_mfma_f32_16x16x32_bf16 v[88:91], v[184:187], v[234:237], v[88:91]
	v_mfma_f32_16x16x32_bf16 v[80:83], v[210:213], v[234:237], v[80:83]
	v_mfma_f32_16x16x32_bf16 v[72:75], v[184:187], v[242:245], v[72:75]
	v_mfma_f32_16x16x32_bf16 v[64:67], v[210:213], v[242:245], v[64:67]
	s_setprio 0
	s_barrier
	s_mov_b32 m0, s37
	s_add_u32 s16, s16, 0x40080
	s_addc_u32 s17, s17, 0
	ds_read_b128 v[214:217], v165 offset:49152
	ds_read_b128 v[218:221], v165 offset:50176
	ds_read_b128 v[222:225], v165 offset:51200
	ds_read_b128 v[226:229], v165 offset:52224
	ds_read_b128 v[230:233], v165 offset:53248
	ds_read_b128 v[234:237], v165 offset:54272
	ds_read_b128 v[238:241], v165 offset:55296
	ds_read_b128 v[242:245], v165 offset:56320
	s_add_u32 s98, s16, 0xfffc0000
	s_addc_u32 s99, s17, -1
	global_load_lds_dwordx4 v132, s[98:99]
	s_mov_b32 m0, s38
	s_nop 0
	global_load_lds_dwordx4 v128, s[98:99]
	s_mov_b32 m0, s41
	s_nop 0
	global_load_lds_dwordx4 v132, s[16:17]
	s_mov_b32 m0, s42
	s_nop 0
	global_load_lds_dwordx4 v128, s[16:17]
	s_mov_b32 m0, s39
	s_nop 0
	s_add_u32 s100, s18, 0xfffc0080
	s_addc_u32 s101, s19, -1
	global_load_lds_dwordx4 v134, s[100:101]
	s_mov_b32 m0, s40
	s_nop 0
	global_load_lds_dwordx4 v130, s[100:101]
	s_waitcnt vmcnt(9)
	s_waitcnt lgkmcnt(0)
	s_barrier
	s_setprio 1
	v_mfma_f32_16x16x32_bf16 v[60:63], v[140:143], v[214:217], v[60:63]
	v_mfma_f32_16x16x32_bf16 v[52:55], v[172:175], v[214:217], v[52:55]
	v_mfma_f32_16x16x32_bf16 v[44:47], v[140:143], v[222:225], v[44:47]
	v_mfma_f32_16x16x32_bf16 v[36:39], v[172:175], v[222:225], v[36:39]
	v_mfma_f32_16x16x32_bf16 v[28:31], v[140:143], v[230:233], v[28:31]
	v_mfma_f32_16x16x32_bf16 v[20:23], v[172:175], v[230:233], v[20:23]
	v_mfma_f32_16x16x32_bf16 v[12:15], v[140:143], v[238:241], v[12:15]
	v_mfma_f32_16x16x32_bf16 v[4:7], v[172:175], v[238:241], v[4:7]
	v_mfma_f32_16x16x32_bf16 v[60:63], v[168:171], v[218:221], v[60:63]
	v_mfma_f32_16x16x32_bf16 v[52:55], v[176:179], v[218:221], v[52:55]
	v_mfma_f32_16x16x32_bf16 v[44:47], v[168:171], v[226:229], v[44:47]
	v_mfma_f32_16x16x32_bf16 v[36:39], v[176:179], v[226:229], v[36:39]
	v_mfma_f32_16x16x32_bf16 v[28:31], v[168:171], v[234:237], v[28:31]
	v_mfma_f32_16x16x32_bf16 v[20:23], v[176:179], v[234:237], v[20:23]
	v_mfma_f32_16x16x32_bf16 v[12:15], v[168:171], v[242:245], v[12:15]
	v_mfma_f32_16x16x32_bf16 v[4:7], v[176:179], v[242:245], v[4:7]
	v_mfma_f32_16x16x32_bf16 v[56:59], v[180:183], v[214:217], v[56:59]
	v_mfma_f32_16x16x32_bf16 v[48:51], v[188:191], v[214:217], v[48:51]
	v_mfma_f32_16x16x32_bf16 v[40:43], v[180:183], v[222:225], v[40:43]
	v_mfma_f32_16x16x32_bf16 v[32:35], v[188:191], v[222:225], v[32:35]
	v_mfma_f32_16x16x32_bf16 v[24:27], v[180:183], v[230:233], v[24:27]
	v_mfma_f32_16x16x32_bf16 v[16:19], v[188:191], v[230:233], v[16:19]
	v_mfma_f32_16x16x32_bf16 v[8:11], v[180:183], v[238:241], v[8:11]
	v_mfma_f32_16x16x32_bf16 v[0:3], v[188:191], v[238:241], v[0:3]
	v_mfma_f32_16x16x32_bf16 v[56:59], v[184:187], v[218:221], v[56:59]
	v_mfma_f32_16x16x32_bf16 v[48:51], v[210:213], v[218:221], v[48:51]
	v_mfma_f32_16x16x32_bf16 v[40:43], v[184:187], v[226:229], v[40:43]
	v_mfma_f32_16x16x32_bf16 v[32:35], v[210:213], v[226:229], v[32:35]
	v_mfma_f32_16x16x32_bf16 v[24:27], v[184:187], v[234:237], v[24:27]
	v_mfma_f32_16x16x32_bf16 v[16:19], v[210:213], v[234:237], v[16:19]
	v_mfma_f32_16x16x32_bf16 v[8:11], v[184:187], v[242:245], v[8:11]
	v_mfma_f32_16x16x32_bf16 v[0:3], v[210:213], v[242:245], v[0:3]
	s_setprio 0
	s_barrier
	s_add_i32 s53, s53, 2
	s_add_u32 s14, s14, 0x100
	s_addc_u32 s15, s15, 0
	s_add_u32 s51, s51, 0x100
	s_addc_u32 s52, s52, 0

; __device__ __forceinline__ unsigned cvt_pk_bf16(float lo, float hi) { unsigned r; asm volatile("v_cvt_pk_bf16_f32 %0, %1, %2" : "=v"(r) : "v"(lo), "v"(hi)); return r; }
;     __device__ __forceinline__ void operator()(const f32x4 (&acc)[2][2][4][2], const Unit& u, int ui, int wr, int wc, int fr, int fq) const {
;     ...
;         const int row0 = u.pm * BM + wr * 64 + fr, col0 = u.pn * HALF + wc * 32 + 8 * fq;
;         float rs[2][4];
; #pragma unroll
;         for (int ai = 0; ai < 2; ++ai)
; #pragma unroll
;             for (int m = 0; m < 4; ++m) rs[ai][m] = row_rstd(lds, ui, ai * HALF + wr * 64 + m * 16 + fr);
; #pragma unroll
;         for (int ai = 0; ai < 2; ++ai)
; #pragma unroll
;             for (int m = 0; m < 4; ++m) { const float r = rs[ai][m]; const int row = row0 + ai * HALF + m * 16;
;                 const float c1 = r * -1.44269504089f, r2 = r * r; u32x4 w;
; #pragma unroll
;                 for (int n = 0; n < 2; ++n)
; #pragma unroll
;                     for (int p = 0; p < 2; ++p) { const f32x2 g = (f32x2){acc[ai][0][m][n][2 * p], acc[ai][0][m][n][2 * p + 1]}, uu = (f32x2){acc[ai][1][m][n][2 * p], acc[ai][1][m][n][2 * p + 1]};
;                         const f32x2 t = g * c1; f32x2 d; d.x = __builtin_amdgcn_exp2f(t.x); d.y = __builtin_amdgcn_exp2f(t.y); d = d + 1.0f;
;                         f32x2 q; q.x = __builtin_amdgcn_rcpf(d.x); q.y = __builtin_amdgcn_rcpf(d.y);
;                         const f32x2 hh = (g * uu) * (q * r2); w[2 * n + p] = cvt_pk_bf16(hh.x, hh.y); }
;                 __builtin_nontemporal_store(w, (u32x4*)(H + (size_t)row * ldh + col0)); }
.LBB0_449:
	v_mov_b32_e32 v140, v147
	v_mov_b32_e32 v167, v164
	v_pk_mul_f32 v[120:121], v[124:125], v[120:121]
	v_add_u32_e32 v171, s35, v140
	v_lshlrev_b32_e32 v140, 2, v171
	v_lshl_add_u32 v140, s48, 10, v140
	v_add_u32_e32 v140, 0x20400, v140
	ds_read2_b32 v[168:169], v140 offset1:16
	ds_read2_b32 v[162:163], v140 offset0:32 offset1:48
	ds_read2_b32 v[142:143], v140 offset0:128 offset1:144
	ds_read2_b32 v[140:141], v140 offset0:160 offset1:176
	v_pk_mul_f32 v[122:123], v[126:127], v[122:123]
	s_waitcnt lgkmcnt(0)
	v_mul_f32_e32 v172, 0xbfb8aa3b, v168
	v_pk_mul_f32 v[174:175], v[124:125], v[172:173] op_sel_hi:[1,0]
	v_pk_mul_f32 v[124:125], v[126:127], v[172:173] op_sel_hi:[1,0]
	v_exp_f32_e32 v174, v174
	v_exp_f32_e32 v175, v175
	v_exp_f32_e32 v124, v124
	v_exp_f32_e32 v125, v125
	v_mul_f32_e32 v168, v168, v168
	v_pk_add_f32 v[174:175], v[174:175], 1.0 op_sel_hi:[1,0]
	v_pk_mul_f32 v[112:113], v[116:117], v[112:113]
	v_rcp_f32_e32 v174, v174
	v_rcp_f32_e32 v175, v175
	v_pk_add_f32 v[124:125], v[124:125], 1.0 op_sel_hi:[1,0]
	v_pk_mul_f32 v[114:115], v[118:119], v[114:115]
	v_rcp_f32_e32 v124, v124
	v_rcp_f32_e32 v125, v125
	v_pk_mul_f32 v[126:127], v[168:169], v[174:175] op_sel_hi:[0,1]
	v_pk_mul_f32 v[120:121], v[120:121], v[126:127]
	v_pk_mul_f32 v[126:127], v[116:117], v[172:173] op_sel_hi:[1,0]
	v_pk_mul_f32 v[124:125], v[168:169], v[124:125] op_sel_hi:[0,1]
	v_exp_f32_e32 v126, v126
	v_exp_f32_e32 v127, v127
	v_pk_mul_f32 v[122:123], v[122:123], v[124:125]
	v_pk_mul_f32 v[124:125], v[118:119], v[172:173] op_sel_hi:[1,0]
	v_cvt_pk_bf16_f32 v120, v120, v121
	v_cvt_pk_bf16_f32 v121, v122, v123
	v_pk_add_f32 v[122:123], v[126:127], 1.0 op_sel_hi:[1,0]
	v_exp_f32_e32 v124, v124
	v_exp_f32_e32 v125, v125
	v_rcp_f32_e32 v122, v122
	v_rcp_f32_e32 v123, v123
	s_lshl_b32 s5, s47, 7
	v_pk_add_f32 v[116:117], v[124:125], 1.0 op_sel_hi:[1,0]
	s_or_b32 s5, s5, s36
	v_rcp_f32_e32 v116, v116
	v_rcp_f32_e32 v117, v117
	v_pk_mul_f32 v[118:119], v[168:169], v[122:123] op_sel_hi:[0,1]
	v_pk_mul_f32 v[112:113], v[112:113], v[118:119]
	v_mul_f32_e32 v118, 0xbfb8aa3b, v169
	v_cvt_pk_bf16_f32 v122, v112, v113
	v_pk_mul_f32 v[112:113], v[168:169], v[116:117] op_sel_hi:[0,1]
	v_pk_mul_f32 v[124:125], v[108:109], v[118:119] op_sel_hi:[1,0]
	v_lshl_add_u32 v170, v167, 3, s5
	v_pk_mul_f32 v[112:113], v[114:115], v[112:113]
	v_exp_f32_e32 v124, v124
	v_exp_f32_e32 v125, v125
	v_lshl_add_u32 v167, s46, 8, v171
	v_mul_lo_u32 v255, v167, s59
	v_lshl_add_u32 v255, v170, 1, v255
	v_cvt_pk_bf16_f32 v123, v112, v113
	v_pk_mul_f32 v[104:105], v[108:109], v[104:105]
	v_pk_mul_f32 v[108:109], v[110:111], v[118:119] op_sel_hi:[1,0]
	v_exp_f32_e32 v108, v108
	v_exp_f32_e32 v109, v109
	s_add_u32 s100, s20, 0x0
	s_addc_u32 s101, s21, 0
	global_store_dwordx4 v255, v[120:123], s[100:101] nt
	v_mul_f32_e32 v116, v169, v169
	v_pk_add_f32 v[108:109], v[108:109], 1.0 op_sel_hi:[1,0]
	v_pk_add_f32 v[120:121], v[124:125], 1.0 op_sel_hi:[1,0]
	v_rcp_f32_e32 v108, v108
	v_rcp_f32_e32 v120, v120
	v_rcp_f32_e32 v121, v121
	v_rcp_f32_e32 v109, v109
	v_pk_mul_f32 v[106:107], v[110:111], v[106:107]
	v_pk_mul_f32 v[96:97], v[100:101], v[96:97]
	v_pk_mul_f32 v[110:111], v[116:117], v[120:121] op_sel_hi:[0,1]
	v_pk_mul_f32 v[104:105], v[104:105], v[110:111]
	v_pk_mul_f32 v[110:111], v[100:101], v[118:119] op_sel_hi:[1,0]
	v_pk_mul_f32 v[108:109], v[116:117], v[108:109] op_sel_hi:[0,1]
	v_exp_f32_e32 v110, v110
	v_exp_f32_e32 v111, v111
	v_pk_mul_f32 v[106:107], v[106:107], v[108:109]
	v_pk_mul_f32 v[108:109], v[102:103], v[118:119] op_sel_hi:[1,0]
	v_cvt_pk_bf16_f32 v104, v104, v105
	v_cvt_pk_bf16_f32 v105, v106, v107
	v_pk_add_f32 v[106:107], v[110:111], 1.0 op_sel_hi:[1,0]
	v_exp_f32_e32 v108, v108
	v_exp_f32_e32 v109, v109
	v_rcp_f32_e32 v106, v106
	v_rcp_f32_e32 v107, v107
	v_pk_mul_f32 v[98:99], v[102:103], v[98:99]
	v_pk_add_f32 v[100:101], v[108:109], 1.0 op_sel_hi:[1,0]
	v_pk_mul_f32 v[88:89], v[92:93], v[88:89]
	v_rcp_f32_e32 v100, v100
	v_rcp_f32_e32 v101, v101
	v_pk_mul_f32 v[102:103], v[116:117], v[106:107] op_sel_hi:[0,1]
	v_pk_mul_f32 v[96:97], v[96:97], v[102:103]
	v_pk_mul_f32 v[90:91], v[94:95], v[90:91]
	v_cvt_pk_bf16_f32 v106, v96, v97
	v_pk_mul_f32 v[96:97], v[116:117], v[100:101] op_sel_hi:[0,1]
	v_pk_mul_f32 v[96:97], v[98:99], v[96:97]
	v_mul_f32_e32 v98, 0xbfb8aa3b, v162
	v_pk_mul_f32 v[100:101], v[92:93], v[98:99] op_sel_hi:[1,0]
	v_pk_mul_f32 v[92:93], v[94:95], v[98:99] op_sel_hi:[1,0]
	v_exp_f32_e32 v100, v100
	v_exp_f32_e32 v101, v101
	v_exp_f32_e32 v92, v92
	v_exp_f32_e32 v93, v93
	v_cvt_pk_bf16_f32 v107, v96, v97
	v_pk_add_f32 v[100:101], v[100:101], 1.0 op_sel_hi:[1,0]
	v_rcp_f32_e32 v100, v100
	v_rcp_f32_e32 v101, v101
	v_pk_add_f32 v[92:93], v[92:93], 1.0 op_sel_hi:[1,0]
	v_rcp_f32_e32 v92, v92
	v_rcp_f32_e32 v93, v93
	s_add_u32 s100, s20, 0x16000
	s_addc_u32 s101, s21, 0
	global_store_dwordx4 v255, v[104:107], s[100:101] nt
	v_mul_f32_e32 v96, v162, v162
; __device__ __forceinline__ unsigned cvt_pk_bf16(float lo, float hi) { unsigned r; asm volatile("v_cvt_pk_bf16_f32 %0, %1, %2" : "=v"(r) : "v"(lo), "v"(hi)); return r; }
;     __device__ __forceinline__ void operator()(const f32x4 (&acc)[2][2][4][2], const Unit& u, int ui, int wr, int wc, int fr, int fq) const {
;     ...
;             for (int m = 0; m < 4; ++m) { const float r = rs[ai][m]; const int row = row0 + ai * HALF + m * 16;
;                 const float c1 = r * -1.44269504089f, r2 = r * r; u32x4 w;
; #pragma unroll
;                 for (int n = 0; n < 2; ++n)
; #pragma unroll
;                     for (int p = 0; p < 2; ++p) { const f32x2 g = (f32x2){acc[ai][0][m][n][2 * p], acc[ai][0][m][n][2 * p + 1]}, uu = (f32x2){acc[ai][1][m][n][2 * p], acc[ai][1][m][n][2 * p + 1]};
;                         const f32x2 t = g * c1; f32x2 d; d.x = __builtin_amdgcn_exp2f(t.x); d.y = __builtin_amdgcn_exp2f(t.y); d = d + 1.0f;
;                         f32x2 q; q.x = __builtin_amdgcn_rcpf(d.x); q.y = __builtin_amdgcn_rcpf(d.y);
;                         const f32x2 hh = (g * uu) * (q * r2); w[2 * n + p] = cvt_pk_bf16(hh.x, hh.y); }
;                 __builtin_nontemporal_store(w, (u32x4*)(H + (size_t)row * ldh + col0)); }
	v_pk_mul_f32 v[94:95], v[96:97], v[100:101] op_sel_hi:[0,1]
	v_pk_mul_f32 v[88:89], v[88:89], v[94:95]
	v_pk_mul_f32 v[94:95], v[84:85], v[98:99] op_sel_hi:[1,0]
	v_pk_mul_f32 v[92:93], v[96:97], v[92:93] op_sel_hi:[0,1]
	v_exp_f32_e32 v94, v94
	v_exp_f32_e32 v95, v95
	v_pk_mul_f32 v[90:91], v[90:91], v[92:93]
	v_pk_mul_f32 v[92:93], v[86:87], v[98:99] op_sel_hi:[1,0]
	v_cvt_pk_bf16_f32 v88, v88, v89
	v_cvt_pk_bf16_f32 v89, v90, v91
	v_pk_add_f32 v[90:91], v[94:95], 1.0 op_sel_hi:[1,0]
	v_exp_f32_e32 v92, v92
	v_exp_f32_e32 v93, v93
	v_rcp_f32_e32 v90, v90
	v_rcp_f32_e32 v91, v91
	v_pk_mul_f32 v[80:81], v[84:85], v[80:81]
	v_pk_add_f32 v[84:85], v[92:93], 1.0 op_sel_hi:[1,0]
	v_pk_mul_f32 v[82:83], v[86:87], v[82:83]
	v_rcp_f32_e32 v84, v84
	v_rcp_f32_e32 v85, v85
	v_pk_mul_f32 v[86:87], v[96:97], v[90:91] op_sel_hi:[0,1]
	v_pk_mul_f32 v[80:81], v[80:81], v[86:87]
	v_pk_mul_f32 v[72:73], v[76:77], v[72:73]
	v_cvt_pk_bf16_f32 v90, v80, v81
	v_pk_mul_f32 v[80:81], v[96:97], v[84:85] op_sel_hi:[0,1]
	v_pk_mul_f32 v[80:81], v[82:83], v[80:81]
	v_mul_f32_e32 v82, 0xbfb8aa3b, v163
	v_pk_mul_f32 v[84:85], v[76:77], v[82:83] op_sel_hi:[1,0]
	v_pk_mul_f32 v[76:77], v[78:79], v[82:83] op_sel_hi:[1,0]
	v_exp_f32_e32 v84, v84
	v_exp_f32_e32 v85, v85
	v_exp_f32_e32 v76, v76
	v_exp_f32_e32 v77, v77
	v_cvt_pk_bf16_f32 v91, v80, v81
	v_pk_add_f32 v[84:85], v[84:85], 1.0 op_sel_hi:[1,0]
	v_rcp_f32_e32 v84, v84
	v_rcp_f32_e32 v85, v85
	v_pk_add_f32 v[76:77], v[76:77], 1.0 op_sel_hi:[1,0]
	v_rcp_f32_e32 v76, v76
	v_rcp_f32_e32 v77, v77
	s_add_u32 s100, s20, 0x2c000
	s_addc_u32 s101, s21, 0
	global_store_dwordx4 v255, v[88:91], s[100:101] nt
	v_mul_f32_e32 v80, v163, v163
	v_pk_mul_f32 v[74:75], v[78:79], v[74:75]
	v_pk_mul_f32 v[78:79], v[80:81], v[84:85] op_sel_hi:[0,1]
	v_pk_mul_f32 v[72:73], v[72:73], v[78:79]
	v_pk_mul_f32 v[78:79], v[68:69], v[82:83] op_sel_hi:[1,0]
	v_pk_mul_f32 v[76:77], v[80:81], v[76:77] op_sel_hi:[0,1]
	v_exp_f32_e32 v78, v78
	v_exp_f32_e32 v79, v79
	v_pk_mul_f32 v[74:75], v[74:75], v[76:77]
	v_pk_mul_f32 v[76:77], v[70:71], v[82:83] op_sel_hi:[1,0]
	v_cvt_pk_bf16_f32 v72, v72, v73
	v_cvt_pk_bf16_f32 v73, v74, v75
	v_pk_add_f32 v[74:75], v[78:79], 1.0 op_sel_hi:[1,0]
	v_exp_f32_e32 v76, v76
	v_exp_f32_e32 v77, v77
	v_rcp_f32_e32 v74, v74
	v_rcp_f32_e32 v75, v75
	v_pk_mul_f32 v[64:65], v[68:69], v[64:65]
	v_pk_add_f32 v[68:69], v[76:77], 1.0 op_sel_hi:[1,0]
	v_pk_mul_f32 v[66:67], v[70:71], v[66:67]
	v_rcp_f32_e32 v68, v68
	v_rcp_f32_e32 v69, v69
	v_pk_mul_f32 v[70:71], v[80:81], v[74:75] op_sel_hi:[0,1]
	v_pk_mul_f32 v[64:65], v[64:65], v[70:71]
	v_pk_mul_f32 v[56:57], v[60:61], v[56:57]
	v_cvt_pk_bf16_f32 v74, v64, v65
	v_pk_mul_f32 v[64:65], v[80:81], v[68:69] op_sel_hi:[0,1]
	v_pk_mul_f32 v[64:65], v[66:67], v[64:65]
	v_mul_f32_e32 v66, 0xbfb8aa3b, v142
	v_pk_mul_f32 v[68:69], v[60:61], v[66:67] op_sel_hi:[1,0]
	v_pk_mul_f32 v[60:61], v[62:63], v[66:67] op_sel_hi:[1,0]
	v_exp_f32_e32 v68, v68
	v_exp_f32_e32 v69, v69
	v_exp_f32_e32 v60, v60
	v_exp_f32_e32 v61, v61
	v_cvt_pk_bf16_f32 v75, v64, v65
	v_pk_add_f32 v[68:69], v[68:69], 1.0 op_sel_hi:[1,0]
	v_rcp_f32_e32 v68, v68
	v_rcp_f32_e32 v69, v69
	v_pk_add_f32 v[60:61], v[60:61], 1.0 op_sel_hi:[1,0]
	v_rcp_f32_e32 v60, v60
	v_rcp_f32_e32 v61, v61
	s_add_u32 s100, s20, 0x42000
	s_addc_u32 s101, s21, 0
	global_store_dwordx4 v255, v[72:75], s[100:101] nt
	v_mul_f32_e32 v64, v142, v142
	v_pk_mul_f32 v[58:59], v[62:63], v[58:59]
	v_pk_mul_f32 v[62:63], v[64:65], v[68:69] op_sel_hi:[0,1]
	v_pk_mul_f32 v[56:57], v[56:57], v[62:63]
	v_pk_mul_f32 v[62:63], v[52:53], v[66:67] op_sel_hi:[1,0]
	v_pk_mul_f32 v[60:61], v[64:65], v[60:61] op_sel_hi:[0,1]
	v_exp_f32_e32 v62, v62
	v_exp_f32_e32 v63, v63
	v_pk_mul_f32 v[58:59], v[58:59], v[60:61]
	v_pk_mul_f32 v[60:61], v[54:55], v[66:67] op_sel_hi:[1,0]
	v_cvt_pk_bf16_f32 v56, v56, v57
	v_cvt_pk_bf16_f32 v57, v58, v59
	v_pk_add_f32 v[58:59], v[62:63], 1.0 op_sel_hi:[1,0]
	v_exp_f32_e32 v60, v60
	v_exp_f32_e32 v61, v61
	v_rcp_f32_e32 v58, v58
	v_rcp_f32_e32 v59, v59
	v_pk_mul_f32 v[48:49], v[52:53], v[48:49]
	v_pk_add_f32 v[52:53], v[60:61], 1.0 op_sel_hi:[1,0]
	v_pk_mul_f32 v[50:51], v[54:55], v[50:51]
	v_rcp_f32_e32 v52, v52
	v_rcp_f32_e32 v53, v53
	v_pk_mul_f32 v[54:55], v[64:65], v[58:59] op_sel_hi:[0,1]
	v_pk_mul_f32 v[48:49], v[48:49], v[54:55]
	v_pk_mul_f32 v[40:41], v[44:45], v[40:41]
	v_cvt_pk_bf16_f32 v58, v48, v49
	v_pk_mul_f32 v[48:49], v[64:65], v[52:53] op_sel_hi:[0,1]
	v_pk_mul_f32 v[48:49], v[50:51], v[48:49]
	v_mul_f32_e32 v50, 0xbfb8aa3b, v143
	v_pk_mul_f32 v[52:53], v[44:45], v[50:51] op_sel_hi:[1,0]
	v_pk_mul_f32 v[44:45], v[46:47], v[50:51] op_sel_hi:[1,0]
	v_exp_f32_e32 v52, v52
	v_exp_f32_e32 v53, v53
	v_exp_f32_e32 v44, v44
	v_exp_f32_e32 v45, v45
	v_cvt_pk_bf16_f32 v59, v48, v49
	v_pk_add_f32 v[52:53], v[52:53], 1.0 op_sel_hi:[1,0]
	v_rcp_f32_e32 v52, v52
	v_rcp_f32_e32 v53, v53
	v_pk_add_f32 v[44:45], v[44:45], 1.0 op_sel_hi:[1,0]
	v_rcp_f32_e32 v44, v44
	v_rcp_f32_e32 v45, v45


; __device__ __forceinline__ unsigned cvt_pk_bf16(float lo, float hi) { unsigned r; asm volatile("v_cvt_pk_bf16_f32 %0, %1, %2" : "=v"(r) : "v"(lo), "v"(hi)); return r; }
;     __device__ __forceinline__ void operator()(const f32x4 (&acc)[2][2][4][2], const Unit& u, int ui, int wr, int wc, int fr, int fq) const {
;     ...
;             for (int m = 0; m < 4; ++m) { const float r = rs[ai][m]; const int row = row0 + ai * HALF + m * 16;
;                 const float c1 = r * -1.44269504089f, r2 = r * r; u32x4 w;
; #pragma unroll
;                 for (int n = 0; n < 2; ++n)
; #pragma unroll
;                     for (int p = 0; p < 2; ++p) { const f32x2 g = (f32x2){acc[ai][0][m][n][2 * p], acc[ai][0][m][n][2 * p + 1]}, uu = (f32x2){acc[ai][1][m][n][2 * p], acc[ai][1][m][n][2 * p + 1]};
;                         const f32x2 t = g * c1; f32x2 d; d.x = __builtin_amdgcn_exp2f(t.x); d.y = __builtin_amdgcn_exp2f(t.y); d = d + 1.0f;
;                         f32x2 q; q.x = __builtin_amdgcn_rcpf(d.x); q.y = __builtin_amdgcn_rcpf(d.y);
;                         const f32x2 hh = (g * uu) * (q * r2); w[2 * n + p] = cvt_pk_bf16(hh.x, hh.y); }
;                 __builtin_nontemporal_store(w, (u32x4*)(H + (size_t)row * ldh + col0)); }
	v_mov_b32_e32 v150, v56
	v_mov_b32_e32 v151, v57
	v_mov_b32_e32 v152, v58
	v_mov_b32_e32 v153, v59
	v_mul_f32_e32 v48, v143, v143
	v_pk_mul_f32 v[42:43], v[46:47], v[42:43]
	v_pk_mul_f32 v[46:47], v[48:49], v[52:53] op_sel_hi:[0,1]
	v_pk_mul_f32 v[40:41], v[40:41], v[46:47]
	v_pk_mul_f32 v[46:47], v[36:37], v[50:51] op_sel_hi:[1,0]
	v_pk_mul_f32 v[44:45], v[48:49], v[44:45] op_sel_hi:[0,1]
	v_exp_f32_e32 v46, v46
	v_exp_f32_e32 v47, v47
	v_pk_mul_f32 v[42:43], v[42:43], v[44:45]
	v_pk_mul_f32 v[44:45], v[38:39], v[50:51] op_sel_hi:[1,0]
	v_cvt_pk_bf16_f32 v40, v40, v41
	v_cvt_pk_bf16_f32 v41, v42, v43
	v_pk_add_f32 v[42:43], v[46:47], 1.0 op_sel_hi:[1,0]
	v_exp_f32_e32 v44, v44
	v_exp_f32_e32 v45, v45
	v_rcp_f32_e32 v42, v42
	v_rcp_f32_e32 v43, v43
	v_pk_mul_f32 v[32:33], v[36:37], v[32:33]
	v_pk_add_f32 v[36:37], v[44:45], 1.0 op_sel_hi:[1,0]
	v_pk_mul_f32 v[34:35], v[38:39], v[34:35]
	v_rcp_f32_e32 v36, v36
	v_rcp_f32_e32 v37, v37
	v_pk_mul_f32 v[38:39], v[48:49], v[42:43] op_sel_hi:[0,1]
	v_pk_mul_f32 v[32:33], v[32:33], v[38:39]
	v_pk_mul_f32 v[24:25], v[28:29], v[24:25]
	v_cvt_pk_bf16_f32 v42, v32, v33
	v_pk_mul_f32 v[32:33], v[48:49], v[36:37] op_sel_hi:[0,1]
	v_pk_mul_f32 v[32:33], v[34:35], v[32:33]
	v_mul_f32_e32 v34, 0xbfb8aa3b, v140
	v_pk_mul_f32 v[36:37], v[28:29], v[34:35] op_sel_hi:[1,0]
	v_pk_mul_f32 v[28:29], v[30:31], v[34:35] op_sel_hi:[1,0]
	v_exp_f32_e32 v36, v36
	v_exp_f32_e32 v37, v37
	v_exp_f32_e32 v28, v28
	v_exp_f32_e32 v29, v29
	v_cvt_pk_bf16_f32 v43, v32, v33
	v_pk_add_f32 v[36:37], v[36:37], 1.0 op_sel_hi:[1,0]
	v_rcp_f32_e32 v36, v36
	v_rcp_f32_e32 v37, v37
	v_pk_add_f32 v[28:29], v[28:29], 1.0 op_sel_hi:[1,0]
	v_rcp_f32_e32 v28, v28
	v_rcp_f32_e32 v29, v29


; __device__ __forceinline__ unsigned cvt_pk_bf16(float lo, float hi) { unsigned r; asm volatile("v_cvt_pk_bf16_f32 %0, %1, %2" : "=v"(r) : "v"(lo), "v"(hi)); return r; }
;     __device__ __forceinline__ void operator()(const f32x4 (&acc)[2][2][4][2], const Unit& u, int ui, int wr, int wc, int fr, int fq) const {
;     ...
;             for (int m = 0; m < 4; ++m) { const float r = rs[ai][m]; const int row = row0 + ai * HALF + m * 16;
;                 const float c1 = r * -1.44269504089f, r2 = r * r; u32x4 w;
; #pragma unroll
;                 for (int n = 0; n < 2; ++n)
; #pragma unroll
;                     for (int p = 0; p < 2; ++p) { const f32x2 g = (f32x2){acc[ai][0][m][n][2 * p], acc[ai][0][m][n][2 * p + 1]}, uu = (f32x2){acc[ai][1][m][n][2 * p], acc[ai][1][m][n][2 * p + 1]};
;                         const f32x2 t = g * c1; f32x2 d; d.x = __builtin_amdgcn_exp2f(t.x); d.y = __builtin_amdgcn_exp2f(t.y); d = d + 1.0f;
;                         f32x2 q; q.x = __builtin_amdgcn_rcpf(d.x); q.y = __builtin_amdgcn_rcpf(d.y);
;                         const f32x2 hh = (g * uu) * (q * r2); w[2 * n + p] = cvt_pk_bf16(hh.x, hh.y); }
;                 __builtin_nontemporal_store(w, (u32x4*)(H + (size_t)row * ldh + col0)); }
	v_mov_b32_e32 v154, v40
	v_mov_b32_e32 v155, v41
	v_mov_b32_e32 v156, v42
	v_mov_b32_e32 v157, v43
	v_mul_f32_e32 v32, v140, v140
	v_pk_mul_f32 v[26:27], v[30:31], v[26:27]
	v_pk_mul_f32 v[30:31], v[32:33], v[36:37] op_sel_hi:[0,1]
	v_pk_mul_f32 v[24:25], v[24:25], v[30:31]
	v_pk_mul_f32 v[30:31], v[20:21], v[34:35] op_sel_hi:[1,0]
	v_pk_mul_f32 v[28:29], v[32:33], v[28:29] op_sel_hi:[0,1]
	v_exp_f32_e32 v30, v30
	v_exp_f32_e32 v31, v31
	v_pk_mul_f32 v[26:27], v[26:27], v[28:29]
	v_pk_mul_f32 v[28:29], v[22:23], v[34:35] op_sel_hi:[1,0]
	v_cvt_pk_bf16_f32 v24, v24, v25
	v_cvt_pk_bf16_f32 v25, v26, v27
	v_pk_add_f32 v[26:27], v[30:31], 1.0 op_sel_hi:[1,0]
	v_exp_f32_e32 v28, v28
	v_exp_f32_e32 v29, v29
	v_rcp_f32_e32 v26, v26
	v_rcp_f32_e32 v27, v27
	v_pk_mul_f32 v[16:17], v[20:21], v[16:17]
	v_pk_add_f32 v[20:21], v[28:29], 1.0 op_sel_hi:[1,0]
	v_pk_mul_f32 v[18:19], v[22:23], v[18:19]
	v_rcp_f32_e32 v20, v20
	v_rcp_f32_e32 v21, v21
	v_pk_mul_f32 v[22:23], v[32:33], v[26:27] op_sel_hi:[0,1]
	v_pk_mul_f32 v[16:17], v[16:17], v[22:23]
	v_pk_mul_f32 v[8:9], v[12:13], v[8:9]
	v_cvt_pk_bf16_f32 v26, v16, v17
	v_pk_mul_f32 v[16:17], v[32:33], v[20:21] op_sel_hi:[0,1]
	v_pk_mul_f32 v[16:17], v[18:19], v[16:17]
	v_mul_f32_e32 v18, 0xbfb8aa3b, v141
	v_pk_mul_f32 v[20:21], v[12:13], v[18:19] op_sel_hi:[1,0]
	v_pk_mul_f32 v[12:13], v[14:15], v[18:19] op_sel_hi:[1,0]
	v_exp_f32_e32 v20, v20
	v_exp_f32_e32 v21, v21
	v_exp_f32_e32 v12, v12
	v_exp_f32_e32 v13, v13
	v_cvt_pk_bf16_f32 v27, v16, v17
	v_pk_add_f32 v[20:21], v[20:21], 1.0 op_sel_hi:[1,0]
	v_rcp_f32_e32 v20, v20
	v_rcp_f32_e32 v21, v21
	v_pk_add_f32 v[12:13], v[12:13], 1.0 op_sel_hi:[1,0]
	v_rcp_f32_e32 v12, v12
	v_rcp_f32_e32 v13, v13


; __device__ __forceinline__ unsigned cvt_pk_bf16(float lo, float hi) { unsigned r; asm volatile("v_cvt_pk_bf16_f32 %0, %1, %2" : "=v"(r) : "v"(lo), "v"(hi)); return r; }
;     __device__ __forceinline__ void operator()(const f32x4 (&acc)[2][2][4][2], const Unit& u, int ui, int wr, int wc, int fr, int fq) const {
;     ...
;             for (int m = 0; m < 4; ++m) { const float r = rs[ai][m]; const int row = row0 + ai * HALF + m * 16;
;                 const float c1 = r * -1.44269504089f, r2 = r * r; u32x4 w;
; #pragma unroll
;                 for (int n = 0; n < 2; ++n)
; #pragma unroll
;                     for (int p = 0; p < 2; ++p) { const f32x2 g = (f32x2){acc[ai][0][m][n][2 * p], acc[ai][0][m][n][2 * p + 1]}, uu = (f32x2){acc[ai][1][m][n][2 * p], acc[ai][1][m][n][2 * p + 1]};
;                         const f32x2 t = g * c1; f32x2 d; d.x = __builtin_amdgcn_exp2f(t.x); d.y = __builtin_amdgcn_exp2f(t.y); d = d + 1.0f;
;                         f32x2 q; q.x = __builtin_amdgcn_rcpf(d.x); q.y = __builtin_amdgcn_rcpf(d.y);
;                         const f32x2 hh = (g * uu) * (q * r2); w[2 * n + p] = cvt_pk_bf16(hh.x, hh.y); }
;                 __builtin_nontemporal_store(w, (u32x4*)(H + (size_t)row * ldh + col0)); }
	v_mov_b32_e32 v158, v24
	v_mov_b32_e32 v159, v25
	v_mov_b32_e32 v160, v26
	v_mov_b32_e32 v161, v27
	v_mul_f32_e32 v16, v141, v141
	v_pk_mul_f32 v[10:11], v[14:15], v[10:11]
	v_pk_mul_f32 v[14:15], v[16:17], v[20:21] op_sel_hi:[0,1]
	v_pk_mul_f32 v[8:9], v[8:9], v[14:15]
	v_pk_mul_f32 v[14:15], v[4:5], v[18:19] op_sel_hi:[1,0]
	v_pk_mul_f32 v[12:13], v[16:17], v[12:13] op_sel_hi:[0,1]
	v_exp_f32_e32 v14, v14
	v_exp_f32_e32 v15, v15
	v_pk_mul_f32 v[10:11], v[10:11], v[12:13]
	v_pk_mul_f32 v[12:13], v[6:7], v[18:19] op_sel_hi:[1,0]
	v_cvt_pk_bf16_f32 v8, v8, v9
	v_cvt_pk_bf16_f32 v9, v10, v11
	v_pk_add_f32 v[10:11], v[14:15], 1.0 op_sel_hi:[1,0]
	v_exp_f32_e32 v12, v12
	v_exp_f32_e32 v13, v13
	v_rcp_f32_e32 v10, v10
	v_rcp_f32_e32 v11, v11
	v_pk_mul_f32 v[0:1], v[4:5], v[0:1]
	v_pk_add_f32 v[4:5], v[12:13], 1.0 op_sel_hi:[1,0]
	v_pk_mul_f32 v[2:3], v[6:7], v[2:3]
	v_rcp_f32_e32 v4, v4
	v_rcp_f32_e32 v5, v5
	v_pk_mul_f32 v[6:7], v[16:17], v[10:11] op_sel_hi:[0,1]
	v_pk_mul_f32 v[0:1], v[0:1], v[6:7]
	s_andn2_b64 vcc, exec, s[8:9]
	v_cvt_pk_bf16_f32 v10, v0, v1
	v_pk_mul_f32 v[0:1], v[16:17], v[4:5] op_sel_hi:[0,1]
	v_pk_mul_f32 v[0:1], v[2:3], v[0:1]
	s_mov_b64 s[8:9], -1
	v_cvt_pk_bf16_f32 v11, v0, v1


; #define PG8_BAR __builtin_amdgcn_s_barrier()
;     __device__ __forceinline__ void operator()(const f32x4 (&acc)[2][2][4][2], const Unit& u, int ui, int wr, int wc, int fr, int fq) const {
;     ...
;                 __builtin_nontemporal_store(w, (u32x4*)(H + (size_t)row * ldh + col0)); }
; template <class Epi, class Sched, bool ALIGN_EPI = false, bool SP2 = false>
; __device__ __forceinline__ void gemm_phase(PG8_LAS unsigned char* lds, const Gemm g, const Sched& S, const Epi& E) {
;     ...
;         if (!has_next) break;
; #pragma unroll
;         for (int a = 0; a < 2; ++a)
; #pragma unroll
;             for (int b = 0; b < 2; ++b)
; #pragma unroll
;                 for (int m = 0; m < 4; ++m)
; #pragma unroll
;                     for (int n = 0; n < 2; ++n) acc[a][b][m][n] = (f32x4){0.f, 0.f, 0.f, 0.f};
;         cur = nxt; cA = nA; cB = nB; ++ui;
;         if constexpr (ALIGN_EPI) { if (wr == 1) PG8_BAR; }
	v_mov_b32_e32 v246, v8
	v_mov_b32_e32 v247, v9
	v_mov_b32_e32 v248, v10
	v_mov_b32_e32 v249, v11
	s_cbranch_vccnz .LBB0_442
	s_andn2_b64 vcc, exec, s[0:1]
	s_cbranch_vccnz .LBB0_441
	s_barrier
	s_branch .LBB0_441

; #define PG8_WAIT_V(n) asm volatile("s_waitcnt vmcnt(" #n ")" ::: "memory")
; #define PG8_BAR __builtin_amdgcn_s_barrier()
;     __device__ __forceinline__ void operator()(const f32x4 (&acc)[2][2][4][2], const Unit& u, int ui, int wr, int wc, int fr, int fq) const {
;     ...
;                 __builtin_nontemporal_store(w, (u32x4*)(H + (size_t)row * ldh + col0)); }
; template <class Epi, class Sched, bool ALIGN_EPI = false, bool SP2 = false>
; __device__ __forceinline__ void gemm_phase(PG8_LAS unsigned char* lds, const Gemm g, const Sched& S, const Epi& E) {
;     ...
;     PG8_WAIT_V(0);
;     if constexpr (!ALIGN_EPI) { if (wr == 0) PG8_BAR; }
;     PG8_BAR;
.LBB0_458:
	s_add_u32 s100, s20, 0xb0000
	s_addc_u32 s101, s21, 0
	global_store_dwordx4 v255, v[150:153], s[100:101] nt
	s_add_u32 s100, s20, 0xc6000
	s_addc_u32 s101, s21, 0
	global_store_dwordx4 v255, v[154:157], s[100:101] nt
	s_add_u32 s100, s20, 0xdc000
	s_addc_u32 s101, s21, 0
	global_store_dwordx4 v255, v[158:161], s[100:101] nt
	s_add_u32 s100, s20, 0xf2000
	s_addc_u32 s101, s21, 0
	global_store_dwordx4 v255, v[246:249], s[100:101] nt
	s_nop 1
	v_mov_b64_e32 v[150:151], 0x200
	v_mov_b64_e32 v[152:153], 0x1ff
	v_mov_b64_e32 v[154:155], 0x400
	v_mov_b64_e32 v[156:157], 0x3ff
	v_mov_b64_e32 v[158:159], 0x300
	v_mov_b64_e32 v[160:161], 0x2ff
	s_waitcnt vmcnt(0)
	v_readlane_b32 s47, v252, 56
	s_mov_b64 s[26:27], 0xb00
	s_mov_b32 s25, s56
	s_mov_b64 s[30:31], 0x200
	s_mov_b64 s[34:35], 0x8000
	s_mov_b32 s76, s57
	s_barrier
